# SB scan: clamp min(80,x) folded into the copy out of the MFMA block (drops 32 canonicalising v_max per tile)
# baseline (speedup 1.0000x reference)
; #define LAS __attribute__((address_space(3)))
; template <bool MK> __device__ __forceinline__ void sb_scan(f32x16& s0, f32x16& s1, int db, int hi, float& R) {
;             f32x16 k0, k1;
; #pragma unroll
;             for (int r = 0; r < 16; ++r) {
;                 const float e0 = ex2(fminf(s0[r], 80.f)), e1 = ex2(fminf(s1[r], 80.f));
;                 const float p0 = rcp(1.0f + e0), p1 = rcp(1.0f + e1);
;                 s0[r] = e0 * p0; s1[r] = e1 * p1;
;                 k0[r] = (!MK || KKOF(0, r) < db) ? p0 : 1.0f; k1[r] = (!MK || KKOF(1, r) < db) ? p1 : 1.0f;
; __device__ __forceinline__ void sb_unit(const Params& p, LAS unsigned char* lds, int b, int hp, int qb, int tid, int lane, int wave) {
;     ...
;     bf16x8 qf[4];
; #pragma unroll
;     for (int d0 = 0; d0 < 4; ++d0) { const v4u raw = *(const v4u*)(Z + tok * ZW + ZQB + h * 64 + d0 * 16 + hi * 8);
;         constexpr float QS = 0.125f * LOG2E;
;         v4u sc; sc.x = pk2(bflo(raw.x) * QS, bfhi(raw.x) * QS); sc.y = pk2(bflo(raw.y) * QS, bfhi(raw.y) * QS);
;         sc.z = pk2(bflo(raw.z) * QS, bfhi(raw.z) * QS); sc.w = pk2(bflo(raw.w) * QS, bfhi(raw.w) * QS);
;         qf[d0] = __builtin_bit_cast(bf16x8, sc); }
;     const bf16* Kb = Z + (size_t)b * S * ZW + ZKB + 2 * hp * 64;
;     const bf16* Vb = Z + (size_t)b * S * ZW + ZVB + 2 * hp * 64;
;     const TrAddr tra = tr_addr(lane);
;     f32x16 o0, o1;
; #pragma unroll
;     for (int r = 0; r < 16; ++r) { o0[r] = 0.f; o1[r] = 0.f; }
;     float R = 1.0f; bool dead = false;
;     const int jtop = 2 * qb + 1, nt = jtop + 1;
;     if (tid < 16) flags[tid] = 0;
;     RING_DRAIN();
;     for (int k = 0; k < 3 && k < nt; ++k) rg.issue4(Kb + (size_t)(jtop - k) * 64 * ZW, Vb + (size_t)(jtop - k) * 64 * ZW, ZW, k);
;     for (int it = 0; it < nt; ++it) {
;         const int j = jtop - it;
;         const int ahead = nt - 1 - it;
;         RING_WAIT4(ahead);
;         if (it > 0) { int alld = 1;
; #pragma unroll
;             for (int w = 0; w < 8; ++w) alld &= flags[((it - 1) & 1) * 8 + w];
;             if (alld) break; }
;         if (it + 3 < nt) rg.issue4(Kb + (size_t)(j - 3) * 64 * ZW, Vb + (size_t)(j - 3) * 64 * ZW, ZW, (it + 3) & 3);
;         if (!dead && 64 * j < tmaxw) {
;             const LAS unsigned char* stg = lds + (it & 3) * (2 * STG_BYTES) + hsel * STG_BYTES;
;             f32x16 s0, s1;
;             qk_tile(stg, qf, col, hi, s0, s1, 0.f);
.LBB0_600:
	s_waitcnt vmcnt(3)
	v_lshlrev_b32_e32 v20, 16, v16
	v_and_b32_e32 v21, 0xffff0000, v16
	s_mov_b32 s0, 0x3e38aa3b
	v_lshlrev_b32_e32 v16, 16, v17
	v_and_b32_e32 v17, 0xffff0000, v17
	v_pk_mul_f32 v[16:17], v[16:17], s[0:1] op_sel_hi:[1,0]
	v_pk_mul_f32 v[20:21], v[20:21], s[0:1] op_sel_hi:[1,0]
	v_cvt_pk_bf16_f32 v69, v16, v17
	v_lshlrev_b32_e32 v16, 16, v18
	v_and_b32_e32 v17, 0xffff0000, v18
	v_pk_mul_f32 v[16:17], v[16:17], s[0:1] op_sel_hi:[1,0]
	s_or_b32 s91, s28, 31
	v_cvt_pk_bf16_f32 v70, v16, v17
	v_lshlrev_b32_e32 v16, 16, v19
	v_and_b32_e32 v17, 0xffff0000, v19
	v_pk_mul_f32 v[16:17], v[16:17], s[0:1] op_sel_hi:[1,0]
	v_cvt_pk_bf16_f32 v68, v20, v21
	v_cvt_pk_bf16_f32 v71, v16, v17
	s_waitcnt vmcnt(2)
	v_lshlrev_b32_e32 v16, 16, v12
	v_and_b32_e32 v17, 0xffff0000, v12
	v_lshlrev_b32_e32 v12, 16, v13
	v_and_b32_e32 v13, 0xffff0000, v13
	v_pk_mul_f32 v[12:13], v[12:13], s[0:1] op_sel_hi:[1,0]
	v_pk_mul_f32 v[16:17], v[16:17], s[0:1] op_sel_hi:[1,0]
	v_cvt_pk_bf16_f32 v73, v12, v13
	v_lshlrev_b32_e32 v12, 16, v14
	v_and_b32_e32 v13, 0xffff0000, v14
	v_pk_mul_f32 v[12:13], v[12:13], s[0:1] op_sel_hi:[1,0]
	v_cvt_pk_bf16_f32 v72, v16, v17
	v_cvt_pk_bf16_f32 v74, v12, v13
	v_lshlrev_b32_e32 v12, 16, v15
	v_and_b32_e32 v13, 0xffff0000, v15
	v_pk_mul_f32 v[12:13], v[12:13], s[0:1] op_sel_hi:[1,0]
	v_lshlrev_b32_e32 v176, 7, v134
	v_cvt_pk_bf16_f32 v75, v12, v13
	s_waitcnt vmcnt(1)
	v_lshlrev_b32_e32 v12, 16, v8
	v_and_b32_e32 v13, 0xffff0000, v8
	v_lshlrev_b32_e32 v8, 16, v9
	v_and_b32_e32 v9, 0xffff0000, v9
	v_pk_mul_f32 v[8:9], v[8:9], s[0:1] op_sel_hi:[1,0]
	v_pk_mul_f32 v[12:13], v[12:13], s[0:1] op_sel_hi:[1,0]
	v_cvt_pk_bf16_f32 v77, v8, v9
	v_lshlrev_b32_e32 v8, 16, v10
	v_and_b32_e32 v9, 0xffff0000, v10
	v_pk_mul_f32 v[8:9], v[8:9], s[0:1] op_sel_hi:[1,0]
	v_cvt_pk_bf16_f32 v76, v12, v13
	v_cvt_pk_bf16_f32 v78, v8, v9
	v_lshlrev_b32_e32 v8, 16, v11
	v_and_b32_e32 v9, 0xffff0000, v11
	v_pk_mul_f32 v[8:9], v[8:9], s[0:1] op_sel_hi:[1,0]
	v_lshlrev_b32_e32 v166, 2, v23
	v_cvt_pk_bf16_f32 v79, v8, v9
	s_waitcnt vmcnt(0)
	v_lshlrev_b32_e32 v8, 16, v4
	v_and_b32_e32 v9, 0xffff0000, v4
	v_lshlrev_b32_e32 v4, 16, v5
	v_and_b32_e32 v5, 0xffff0000, v5
	v_pk_mul_f32 v[4:5], v[4:5], s[0:1] op_sel_hi:[1,0]
	v_pk_mul_f32 v[8:9], v[8:9], s[0:1] op_sel_hi:[1,0]
	v_cvt_pk_bf16_f32 v81, v4, v5
	v_lshlrev_b32_e32 v4, 16, v6
	v_and_b32_e32 v5, 0xffff0000, v6
	v_pk_mul_f32 v[4:5], v[4:5], s[0:1] op_sel_hi:[1,0]
	v_and_b32_e32 v6, 2, v24
	v_cvt_pk_bf16_f32 v82, v4, v5
	v_lshlrev_b32_e32 v4, 16, v7
	v_and_b32_e32 v5, 0xffff0000, v7
	v_pk_mul_f32 v[4:5], v[4:5], s[0:1] op_sel_hi:[1,0]
	v_bfe_u32 v7, v22, 1, 1
	v_cvt_pk_bf16_f32 v83, v4, v5
	v_xor_b32_e32 v4, v23, v25
	v_lshlrev_b32_e32 v178, 4, v4
	v_bitop3_b32 v4, v23, v25, 2 bitop3:0x36
	v_lshlrev_b32_e32 v179, 4, v4
	v_bitop3_b32 v4, v23, v25, 4 bitop3:0x36
	v_lshlrev_b32_e32 v180, 4, v4
	v_bitop3_b32 v4, v23, v25, 6 bitop3:0x36
	v_lshlrev_b32_e32 v181, 4, v4
	v_bfe_u32 v4, v22, 2, 2
	v_cvt_pk_bf16_f32 v80, v8, v9
	s_lshl_b32 s0, s8, 6
	v_and_or_b32 v4, v24, 4, v4
	v_or_b32_e32 v8, v6, v7
	s_or_b32 s0, s0, 64
	v_lshlrev_b32_e32 v5, 3, v135
	v_bitop3_b32 v6, v6, v4, v7 bitop3:0x36
	v_bitop3_b32 v7, v8, v4, 4 bitop3:0x36
	v_cmp_gt_u32_e64 s[18:19], 32, v135
	s_cmp_ge_u32 s0, s91
	v_lshlrev_b32_e32 v182, 7, v4
	v_and_b32_e32 v183, 8, v5
	v_lshlrev_b32_e32 v184, 4, v6
	v_lshlrev_b32_e32 v185, 4, v7
	v_writelane_b32 v250, s28, 31
	v_writelane_b32 v250, s10, 35
	s_cbranch_scc1 .LBB0_606
	v_add_u32_e32 v37, s31, v176
	v_add_u32_e32 v20, v37, v178
	ds_read_b128 v[4:7], v20
	v_add_u32_e32 v38, v37, v179
	ds_read_b128 v[42:45], v38
	ds_read_b128 v[20:23], v20 offset:4096
	s_or_b32 s4, s0, 63
	s_cmp_lt_u32 s4, s28
	s_mov_b64 s[20:21], -1
	s_waitcnt lgkmcnt(2)
	v_mfma_f32_32x32x16_bf16 v[4:19], v[4:7], v[68:71], 0
	s_waitcnt lgkmcnt(1)
	v_mfma_f32_32x32x16_bf16 v[4:19], v[42:45], v[72:75], v[4:19]
	ds_read_b128 v[42:45], v38 offset:4096
	v_add_u32_e32 v38, v37, v180
	v_add_u32_e32 v37, v37, v181
	s_waitcnt lgkmcnt(1)
	v_mfma_f32_32x32x16_bf16 v[20:35], v[20:23], v[68:71], 0
	s_waitcnt lgkmcnt(0)
	v_mfma_f32_32x32x16_bf16 v[20:35], v[42:45], v[72:75], v[20:35]
	ds_read_b128 v[42:45], v38
	s_waitcnt lgkmcnt(0)
	v_mfma_f32_32x32x16_bf16 v[4:19], v[42:45], v[76:79], v[4:19]
	ds_read_b128 v[42:45], v38 offset:4096
	s_waitcnt lgkmcnt(0)
	v_mfma_f32_32x32x16_bf16 v[20:35], v[42:45], v[76:79], v[20:35]
	ds_read_b128 v[42:45], v37
	s_waitcnt lgkmcnt(0)
	v_mfma_f32_32x32x16_bf16 v[4:19], v[42:45], v[80:83], v[4:19]
	ds_read_b128 v[42:45], v37 offset:4096
	s_waitcnt lgkmcnt(0)
	v_mfma_f32_32x32x16_bf16 v[20:35], v[42:45], v[80:83], v[20:35]
	s_nop 8
	v_min_f32_e32 v186, 0x42a00000, v4
	v_min_f32_e32 v165, 0x42a00000, v5
	v_min_f32_e32 v163, 0x42a00000, v6
	v_min_f32_e32 v161, 0x42a00000, v7
	v_min_f32_e32 v159, 0x42a00000, v8
	v_min_f32_e32 v157, 0x42a00000, v9
	v_min_f32_e32 v155, 0x42a00000, v10
	v_min_f32_e32 v187, 0x42a00000, v20
	v_min_f32_e32 v164, 0x42a00000, v21
	v_min_f32_e32 v162, 0x42a00000, v22
	v_min_f32_e32 v160, 0x42a00000, v23
	v_min_f32_e32 v158, 0x42a00000, v24
	v_min_f32_e32 v156, 0x42a00000, v25
	v_min_f32_e32 v154, 0x42a00000, v26
	v_min_f32_e32 v153, 0x42a00000, v11
	v_min_f32_e32 v152, 0x42a00000, v27
	v_min_f32_e32 v151, 0x42a00000, v12
	v_min_f32_e32 v150, 0x42a00000, v28
	v_min_f32_e32 v149, 0x42a00000, v13
	v_min_f32_e32 v148, 0x42a00000, v29
	v_min_f32_e32 v147, 0x42a00000, v14
	v_min_f32_e32 v146, 0x42a00000, v30
	v_min_f32_e32 v145, 0x42a00000, v15
	v_min_f32_e32 v144, 0x42a00000, v31
	v_min_f32_e32 v143, 0x42a00000, v16
	v_min_f32_e32 v142, 0x42a00000, v32
	v_min_f32_e32 v141, 0x42a00000, v17
	v_min_f32_e32 v140, 0x42a00000, v33
	v_min_f32_e32 v139, 0x42a00000, v18
	v_min_f32_e32 v138, 0x42a00000, v34
	v_min_f32_e32 v137, 0x42a00000, v19
	v_min_f32_e32 v136, 0x42a00000, v35
	s_cbranch_scc1 .LBB0_603
; template <bool MK> __device__ __forceinline__ void sb_scan(f32x16& s0, f32x16& s1, int db, int hi, float& R) {
;             f32x16 k0, k1;
; #pragma unroll
;             for (int r = 0; r < 16; ++r) {
;                 const float e0 = ex2(fminf(s0[r], 80.f)), e1 = ex2(fminf(s1[r], 80.f));
;                 const float p0 = rcp(1.0f + e0), p1 = rcp(1.0f + e1);
;                 s0[r] = e0 * p0; s1[r] = e1 * p1;
;                 k0[r] = (!MK || KKOF(0, r) < db) ? p0 : 1.0f; k1[r] = (!MK || KKOF(1, r) < db) ? p1 : 1.0f;
;             }
;             float g4[8], pg[8], E[8];
; #pragma unroll
;             for (int k4 = 0; k4 < 4; ++k4) { g4[k4] = (k0[4 * k4] * k0[4 * k4 + 1]) * (k0[4 * k4 + 2] * k0[4 * k4 + 3]); g4[4 + k4] = (k1[4 * k4] * k1[4 * k4 + 1]) * (k1[4 * k4 + 2] * k1[4 * k4 + 3]); }
; #pragma unroll
;             for (int G = 0; G < 8; ++G) pg[G] = __shfl_xor(g4[G], 32);
;             E[7] = 1.0f;
; #pragma unroll
;             for (int G = 6; G >= 0; --G) E[G] = E[G + 1] * (g4[G + 1] * pg[G + 1]);
;             const float T = E[0] * (g4[0] * pg[0]);
; #pragma unroll
;             for (int G = 0; G < 8; ++G) {
;                 const float base = R * E[G] * (hi == 0 ? pg[G] : 1.0f);
;                 const int k4 = G & 3;
;                 if (G < 4) {
;                     const float u3 = base, u2 = u3 * k0[4 * k4 + 3], u1 = u2 * k0[4 * k4 + 2], u0 = u1 * k0[4 * k4 + 1];
;                     s0[4 * k4 + 3] = (!MK || KKOF(0, 4 * k4 + 3) < db) ? s0[4 * k4 + 3] * u3 : 0.f;
;                     s0[4 * k4 + 2] = (!MK || KKOF(0, 4 * k4 + 2) < db) ? s0[4 * k4 + 2] * u2 : 0.f;
;                     s0[4 * k4 + 1] = (!MK || KKOF(0, 4 * k4 + 1) < db) ? s0[4 * k4 + 1] * u1 : 0.f;
;                     s0[4 * k4 + 0] = (!MK || KKOF(0, 4 * k4 + 0) < db) ? s0[4 * k4 + 0] * u0 : 0.f;
;                 } else {
;                     const float u3 = base, u2 = u3 * k1[4 * k4 + 3], u1 = u2 * k1[4 * k4 + 2], u0 = u1 * k1[4 * k4 + 1];
;                     s1[4 * k4 + 3] = (!MK || KKOF(1, 4 * k4 + 3) < db) ? s1[4 * k4 + 3] * u3 : 0.f;
;                     s1[4 * k4 + 2] = (!MK || KKOF(1, 4 * k4 + 2) < db) ? s1[4 * k4 + 2] * u2 : 0.f;
;                     s1[4 * k4 + 1] = (!MK || KKOF(1, 4 * k4 + 1) < db) ? s1[4 * k4 + 1] * u1 : 0.f;
;                     s1[4 * k4 + 0] = (!MK || KKOF(1, 4 * k4 + 0) < db) ? s1[4 * k4 + 0] * u0 : 0.f;
;                 }
	v_exp_f32_e32 v66, v149
	v_exp_f32_e32 v21, v148
	v_or_b32_e32 v4, s0, v166
	v_add_f32_e32 v23, 1.0, v66
	v_rcp_f32_e32 v88, v23
	v_add_f32_e32 v23, 1.0, v21
	v_rcp_f32_e32 v23, v23
	v_sub_u32_e32 v7, v36, v4
	v_cmp_lt_i32_e64 s[50:51], 50, v7
	v_mul_f32_e32 v87, v21, v23
	v_exp_f32_e32 v98, v147
	v_exp_f32_e32 v21, v146
	v_exp_f32_e32 v92, v140
	v_add_f32_e32 v25, 1.0, v98
	v_rcp_f32_e32 v104, v25
	v_add_f32_e32 v25, 1.0, v21
	v_rcp_f32_e32 v25, v25
	v_exp_f32_e32 v50, v157
	v_mul_f32_e32 v97, v21, v25
	v_cndmask_b32_e64 v121, 1.0, v25, s[50:51]
	v_exp_f32_e32 v25, v141
	v_exp_f32_e32 v30, v156
	v_add_f32_e32 v29, 1.0, v92
	v_rcp_f32_e32 v96, v29
	v_add_f32_e32 v27, 1.0, v25
	v_rcp_f32_e32 v27, v27
	v_add_f32_e32 v17, 1.0, v50
	v_exp_f32_e32 v16, v186
	v_mul_f32_e32 v29, v25, v27
	v_exp_f32_e32 v25, v139
	v_rcp_f32_e32 v52, v17
	v_add_f32_e32 v17, 1.0, v30
	v_exp_f32_e32 v4, v187
	v_rcp_f32_e32 v36, v17
	v_exp_f32_e32 v116, v145
	v_exp_f32_e32 v60, v155
	v_exp_f32_e32 v118, v144
	v_exp_f32_e32 v108, v138
	v_add_f32_e32 v33, 1.0, v25
	v_exp_f32_e32 v42, v154
	v_rcp_f32_e32 v33, v33
	v_add_f32_e32 v5, 1.0, v16
	v_rcp_f32_e32 v20, v5
	v_add_f32_e32 v5, 1.0, v4
	v_add_f32_e32 v21, 1.0, v116
	v_rcp_f32_e32 v6, v5
	v_add_f32_e32 v17, 1.0, v60
	v_rcp_f32_e32 v114, v21
	v_add_f32_e32 v21, 1.0, v118
	v_exp_f32_e32 v26, v165
	v_exp_f32_e32 v38, v163
	v_exp_f32_e32 v102, v161
	v_rcp_f32_e32 v64, v17
	v_add_f32_e32 v17, 1.0, v42
	v_rcp_f32_e32 v128, v21
	v_mul_f32_e32 v37, v25, v33
	v_exp_f32_e32 v8, v164
	v_exp_f32_e32 v12, v162
	v_exp_f32_e32 v24, v160
	v_rcp_f32_e32 v48, v17
	v_exp_f32_e32 v117, v143
	v_exp_f32_e32 v126, v137
	v_exp_f32_e32 v90, v153
	v_exp_f32_e32 v62, v142
	v_exp_f32_e32 v25, v136
	v_exp_f32_e32 v112, v152
	v_add_f32_e32 v5, 1.0, v26
	v_add_f32_e32 v9, 1.0, v38
	v_add_f32_e32 v13, 1.0, v102
	v_cmp_lt_i32_e64 s[68:69], 26, v7
	v_rcp_f32_e32 v32, v5
	v_add_f32_e32 v5, 1.0, v8
	v_rcp_f32_e32 v44, v9
	v_add_f32_e32 v9, 1.0, v12
	v_rcp_f32_e32 v100, v13
	v_add_f32_e32 v13, 1.0, v24
	v_add_f32_e32 v21, 1.0, v117
	v_cndmask_b32_e64 v124, 1.0, v33, s[68:69]
	v_add_f32_e32 v33, 1.0, v126
	v_rcp_f32_e32 v10, v5
	v_rcp_f32_e32 v14, v9
	v_rcp_f32_e32 v28, v13
	v_add_f32_e32 v17, 1.0, v90
	v_rcp_f32_e32 v115, v21
	v_add_f32_e32 v21, 1.0, v62
	v_add_f32_e32 v35, 1.0, v108
	v_rcp_f32_e32 v130, v33
	v_add_f32_e32 v33, 1.0, v25
	v_rcp_f32_e32 v94, v17
	v_add_f32_e32 v17, 1.0, v112
	v_rcp_f32_e32 v86, v21
	v_rcp_f32_e32 v106, v35
	v_rcp_f32_e32 v33, v33
	v_rcp_f32_e32 v110, v17
	v_cmp_lt_i32_e32 vcc, 32, v7
	v_cmp_lt_i32_e64 s[20:21], 33, v7
	v_cmp_lt_i32_e64 s[22:23], 34, v7
	v_cmp_lt_i32_e64 s[28:29], 35, v7
	v_exp_f32_e32 v56, v151
	v_cndmask_b32_e32 v11, 1.0, v6, vcc
	v_cndmask_b32_e64 v5, 1.0, v10, s[20:21]
	v_cndmask_b32_e64 v9, 1.0, v14, s[22:23]
	v_cndmask_b32_e64 v13, 1.0, v28, s[28:29]
	v_exp_f32_e32 v113, v150
	v_cmp_lt_i32_e64 s[54:55], 56, v7
	v_cmp_lt_i32_e64 s[58:59], 57, v7
	v_cmp_lt_i32_e64 s[62:63], 58, v7
	v_cmp_lt_i32_e64 s[66:67], 59, v7
	v_cndmask_b32_e64 v21, 1.0, v86, s[54:55]
	v_cndmask_b32_e64 v63, 1.0, v96, s[58:59]
	v_cndmask_b32_e64 v93, 1.0, v106, s[62:63]
	v_mul_f32_e32 v210, v25, v33
	v_cndmask_b32_e64 v109, 1.0, v33, s[66:67]
	v_mul_f32_e32 v11, v11, v5
	v_mul_f32_e32 v25, v9, v13
	v_mul_f32_e32 v205, v11, v25
	v_mul_f32_e32 v21, v21, v63
	v_mul_f32_e32 v25, v93, v109
	v_add_f32_e32 v17, 1.0, v56
	v_mul_f32_e32 v21, v21, v25
	v_exp_f32_e32 v103, v159
	v_rcp_f32_e32 v58, v17
	v_add_f32_e32 v17, 1.0, v113
	ds_bpermute_b32 v107, v201, v21
	v_exp_f32_e32 v18, v158
	v_rcp_f32_e32 v111, v17
	v_add_f32_e32 v15, 1.0, v103
	v_cmp_lt_i32_e64 s[42:43], 49, v7
	v_cmp_lt_i32_e64 s[56:57], 51, v7
	v_cmp_lt_i32_e64 s[70:71], 48, v7
	v_rcp_f32_e32 v101, v15
	v_add_f32_e32 v15, 1.0, v18
	v_cndmask_b32_e64 v133, 1.0, v128, s[56:57]
	s_waitcnt lgkmcnt(0)
	v_mul_f32_e32 v129, v21, v107
	v_cndmask_b32_e64 v21, 1.0, v111, s[70:71]
	v_cndmask_b32_e64 v123, 1.0, v23, s[42:43]
	v_rcp_f32_e32 v22, v15
	v_mul_f32_e32 v33, v121, v133
	v_mul_f32_e32 v21, v21, v123
	v_mul_f32_e32 v208, v21, v33
	ds_bpermute_b32 v132, v201, v208
	v_cmp_lt_i32_e64 s[26:27], 40, v7
	v_cmp_lt_i32_e64 s[34:35], 41, v7
	v_cmp_lt_i32_e64 s[38:39], 42, v7
	v_cmp_lt_i32_e64 s[72:73], 43, v7
	v_cndmask_b32_e64 v15, 1.0, v22, s[26:27]
	v_cndmask_b32_e64 v19, 1.0, v36, s[34:35]
	v_cndmask_b32_e64 v31, 1.0, v48, s[38:39]
	v_cndmask_b32_e64 v43, 1.0, v110, s[72:73]
	v_mul_f32_e32 v15, v15, v19
	v_mul_f32_e32 v35, v31, v43
	v_mul_f32_e32 v15, v15, v35
	ds_bpermute_b32 v35, v201, v15
	s_waitcnt lgkmcnt(1)
	v_cndmask_b32_e64 v119, 1.0, v132, s[18:19]
	ds_bpermute_b32 v207, v201, v205
	v_pk_mul_f32 v[112:113], v[112:113], v[110:111]
	v_pk_mul_f32 v[110:111], v[118:119], v[128:129]
	v_cmp_lt_i32_e64 s[64:65], 25, v7
	v_mov_b32_e32 v209, v111
	v_pk_mul_f32 v[118:119], v[208:209], v[132:133]
	v_mov_b32_e32 v120, v129
	v_cmp_lt_i32_e64 s[76:77], 24, v7
	v_cmp_lt_i32_e64 s[74:75], 27, v7
	v_pk_mul_f32 v[120:121], v[120:121], v[118:119]
	v_pk_mul_f32 v[116:117], v[116:117], v[114:115]
	v_cndmask_b32_e64 v204, 1.0, v115, s[76:77]
	v_cndmask_b32_e64 v115, 1.0, v27, s[64:65]
	v_cndmask_b32_e64 v202, 1.0, v130, s[74:75]
	s_waitcnt lgkmcnt(1)
	v_mul_f32_e32 v125, v15, v35
	v_mov_b32_e32 v203, v120
	v_mov_b32_e32 v206, v115
	v_pk_mul_f32 v[128:129], v[124:125], v[202:203]
	s_waitcnt lgkmcnt(0)
; template <bool MK> __device__ __forceinline__ void sb_scan(f32x16& s0, f32x16& s1, int db, int hi, float& R) {
;     ...
;             float g4[8], pg[8], E[8];
; #pragma unroll
;             for (int k4 = 0; k4 < 4; ++k4) { g4[k4] = (k0[4 * k4] * k0[4 * k4 + 1]) * (k0[4 * k4 + 2] * k0[4 * k4 + 3]); g4[4 + k4] = (k1[4 * k4] * k1[4 * k4 + 1]) * (k1[4 * k4 + 2] * k1[4 * k4 + 3]); }
; #pragma unroll
;             for (int G = 0; G < 8; ++G) pg[G] = __shfl_xor(g4[G], 32);
;             E[7] = 1.0f;
; #pragma unroll
;             for (int G = 6; G >= 0; --G) E[G] = E[G + 1] * (g4[G + 1] * pg[G + 1]);
;             const float T = E[0] * (g4[0] * pg[0]);
; #pragma unroll
;             for (int G = 0; G < 8; ++G) {
;                 const float base = R * E[G] * (hi == 0 ? pg[G] : 1.0f);
;                 const int k4 = G & 3;
;                 if (G < 4) {
;                     const float u3 = base, u2 = u3 * k0[4 * k4 + 3], u1 = u2 * k0[4 * k4 + 2], u0 = u1 * k0[4 * k4 + 1];
;                     s0[4 * k4 + 3] = (!MK || KKOF(0, 4 * k4 + 3) < db) ? s0[4 * k4 + 3] * u3 : 0.f;
;                     s0[4 * k4 + 2] = (!MK || KKOF(0, 4 * k4 + 2) < db) ? s0[4 * k4 + 2] * u2 : 0.f;
;                     s0[4 * k4 + 1] = (!MK || KKOF(0, 4 * k4 + 1) < db) ? s0[4 * k4 + 1] * u1 : 0.f;
;                     s0[4 * k4 + 0] = (!MK || KKOF(0, 4 * k4 + 0) < db) ? s0[4 * k4 + 0] * u0 : 0.f;
;                 } else {
;                     const float u3 = base, u2 = u3 * k1[4 * k4 + 3], u1 = u2 * k1[4 * k4 + 2], u0 = u1 * k1[4 * k4 + 1];
;                     s1[4 * k4 + 3] = (!MK || KKOF(1, 4 * k4 + 3) < db) ? s1[4 * k4 + 3] * u3 : 0.f;
;                     s1[4 * k4 + 2] = (!MK || KKOF(1, 4 * k4 + 2) < db) ? s1[4 * k4 + 2] * u2 : 0.f;
;                     s1[4 * k4 + 1] = (!MK || KKOF(1, 4 * k4 + 1) < db) ? s1[4 * k4 + 1] * u1 : 0.f;
;                     s1[4 * k4 + 0] = (!MK || KKOF(1, 4 * k4 + 0) < db) ? s1[4 * k4 + 0] * u0 : 0.f;
;                 }
;             }
;             R *= T;
	v_pk_mul_f32 v[204:205], v[204:205], v[206:207]
	v_cmp_lt_i32_e64 s[46:47], 16, v7
	v_pk_mul_f32 v[204:205], v[204:205], v[128:129]
	ds_bpermute_b32 v206, v201, v204
	v_cmp_lt_i32_e64 s[52:53], 17, v7
	v_cmp_lt_i32_e64 s[60:61], 18, v7
	v_cmp_lt_i32_e64 s[82:83], 19, v7
	v_cmp_lt_i32_e64 s[40:41], 9, v7
	v_cmp_lt_i32_e64 s[44:45], 10, v7
	v_cmp_lt_i32_e64 s[48:49], 11, v7
	v_cndmask_b32_e64 v17, 1.0, v58, s[46:47]
	v_cndmask_b32_e64 v57, 1.0, v88, s[52:53]
	v_cndmask_b32_e64 v67, 1.0, v104, s[60:61]
	v_cmp_lt_i32_e64 s[78:79], 8, v7
	v_cndmask_b32_e64 v99, 1.0, v114, s[82:83]
	v_cmp_lt_i32_e64 s[24:25], 0, v7
	v_cmp_lt_i32_e64 s[30:31], 1, v7
	v_cmp_lt_i32_e64 s[36:37], 2, v7
	v_cndmask_b32_e64 v51, 1.0, v64, s[44:45]
	v_cndmask_b32_e64 v61, 1.0, v94, s[48:49]
	v_mul_f32_e32 v17, v17, v57
	v_cmp_lt_i32_e64 s[80:81], 3, v7
	v_pk_mul_f32 v[102:103], v[102:103], v[100:101]
	v_cndmask_b32_e64 v15, 1.0, v101, s[78:79]
	v_cndmask_b32_e64 v101, 1.0, v52, s[40:41]
	v_mul_f32_e32 v7, v67, v99
	v_mul_f32_e32 v11, v51, v61
	v_mul_f32_e32 v15, v15, v101
	v_mul_f32_e32 v7, v17, v7
	v_mul_f32_e32 v55, v15, v11
	ds_bpermute_b32 v11, v201, v7
	s_waitcnt lgkmcnt(1)
	v_cndmask_b32_e64 v127, 1.0, v206, s[18:19]
	v_mov_b32_e32 v131, v205
	v_cndmask_b32_e64 v122, 1.0, v35, s[18:19]
	ds_bpermute_b32 v35, v201, v55
	v_pk_mul_f32 v[126:127], v[126:127], v[130:131]
	v_cndmask_b32_e64 v25, 1.0, v207, s[18:19]
	v_mov_b32_e32 v130, v204
	v_mov_b32_e32 v131, v127
	v_mov_b32_e32 v207, v202
	v_pk_mul_f32 v[130:131], v[130:131], v[206:207]
	v_mov_b32_e32 v202, v205
	v_mov_b32_e32 v203, v124
	v_pk_mul_f32 v[124:125], v[130:131], v[202:203]
	v_cndmask_b32_e64 v54, 1.0, v20, s[24:25]
	v_cndmask_b32_e64 v34, 1.0, v32, s[30:31]
	v_cndmask_b32_e64 v46, 1.0, v44, s[36:37]
	v_cndmask_b32_e64 v132, 1.0, v100, s[80:81]
	s_waitcnt lgkmcnt(1)
	v_mul_f32_e32 v47, v7, v11
	v_mov_b32_e32 v133, v124
	s_waitcnt lgkmcnt(0)
	v_pk_mul_f32 v[54:55], v[54:55], v[34:35]
	v_pk_mul_f32 v[202:203], v[46:47], v[132:133]
	v_cndmask_b32_e64 v91, 1.0, v35, s[18:19]
	v_pk_mul_f32 v[54:55], v[54:55], v[202:203]
	v_mov_b32_e32 v95, v203
	ds_bpermute_b32 v118, v201, v54
	v_pk_mul_f32 v[90:91], v[90:91], v[94:95]
	v_mov_b32_e32 v39, v132
	v_mov_b32_e32 v65, v91
	v_pk_mul_f32 v[60:61], v[60:61], v[64:65]
	s_waitcnt lgkmcnt(0)
	v_cndmask_b32_e64 v100, 1.0, v118, s[18:19]
	v_mov_b32_e32 v53, v61
	v_pk_mul_f32 v[50:51], v[50:51], v[52:53]
	v_mov_b32_e32 v52, v55
	v_mov_b32_e32 v53, v51
	v_pk_mul_f32 v[52:53], v[100:101], v[52:53]
	v_mov_b32_e32 v27, v46
	v_mov_b32_e32 v45, v52
	v_pk_mul_f32 v[38:39], v[38:39], v[44:45]
	v_cndmask_b32_e64 v114, 1.0, v11, s[18:19]
	v_mov_b32_e32 v33, v39
	v_pk_mul_f32 v[26:27], v[26:27], v[32:33]
	v_mov_b32_e32 v17, v34
	v_mov_b32_e32 v21, v27
	v_mul_f32_e32 v7, v38, v39
	v_pk_mul_f32 v[20:21], v[16:17], v[20:21]
	v_cndmask_b32_e64 v16, 0, v7, s[36:37]
	v_mul_f32_e32 v7, v26, v27
	v_pk_mul_f32 v[38:39], v[114:115], v[124:125]
	v_cndmask_b32_e64 v33, 0, v7, s[30:31]
	v_mul_f32_e32 v7, v20, v21
	v_mov_b32_e32 v105, v38
	v_cndmask_b32_e64 v32, 0, v7, s[24:25]
	v_pk_mul_f32 v[20:21], v[102:103], v[52:53]
	v_mul_f32_e32 v7, v90, v91
	v_pk_mul_f32 v[34:35], v[98:99], v[104:105]
	v_cndmask_b32_e64 v26, 0, v21, s[78:79]
	v_cndmask_b32_e64 v21, 0, v7, s[48:49]
	v_mul_f32_e32 v7, v60, v61
	v_mov_b32_e32 v89, v35
	v_cndmask_b32_e64 v17, 0, v20, s[80:81]
	v_cndmask_b32_e64 v20, 0, v7, s[44:45]
	v_mul_f32_e32 v7, v50, v51
	v_pk_mul_f32 v[44:45], v[66:67], v[88:89]
	v_cndmask_b32_e64 v27, 0, v7, s[40:41]
	v_mov_b32_e32 v59, v45
	v_mul_f32_e32 v7, v34, v35
	v_pk_mul_f32 v[50:51], v[56:57], v[58:59]
	v_cndmask_b32_e64 v34, 0, v7, s[60:61]
	v_mul_f32_e32 v7, v44, v45
	v_cndmask_b32_e64 v47, 0, v7, s[52:53]
	v_mul_f32_e32 v7, v50, v51
	v_cndmask_b32_e64 v46, 0, v7, s[46:47]
	v_mul_f32_e32 v7, v126, v127
	v_cndmask_b32_e64 v45, 0, v7, s[74:75]
	v_mul_f32_e32 v7, v37, v131
	v_cndmask_b32_e64 v44, 0, v7, s[68:69]
	v_mul_f32_e32 v7, v29, v125
	v_mov_b32_e32 v29, v129
	v_pk_mul_f32 v[24:25], v[24:25], v[28:29]
	v_pk_mul_f32 v[38:39], v[116:117], v[38:39]
	v_mov_b32_e32 v15, v25
	v_pk_mul_f32 v[12:13], v[12:13], v[14:15]
	v_cndmask_b32_e64 v35, 0, v38, s[82:83]
	v_mov_b32_e32 v11, v13
	v_pk_mul_f32 v[8:9], v[8:9], v[10:11]
	v_cndmask_b32_e64 v38, 0, v39, s[76:77]
	v_cndmask_b32_e64 v39, 0, v7, s[64:65]
	v_mov_b32_e32 v7, v9
	v_pk_mul_f32 v[10:11], v[4:5], v[6:7]
	v_mul_f32_e32 v4, v24, v25
	v_cndmask_b32_e64 v5, 0, v4, s[28:29]
	v_mul_f32_e32 v4, v12, v13
	v_pk_mul_f32 v[12:13], v[122:123], v[120:121]
	v_mul_f32_e32 v6, v8, v9
	v_mov_b32_e32 v49, v12
	v_pk_mul_f32 v[8:9], v[42:43], v[48:49]
	v_cndmask_b32_e64 v7, 0, v6, s[20:21]
	v_mov_b32_e32 v37, v9
	v_mul_f32_e32 v6, v10, v11
	v_pk_mul_f32 v[10:11], v[30:31], v[36:37]
	v_mul_f32_e32 v8, v8, v9
	v_mov_b32_e32 v23, v11
	v_pk_mul_f32 v[14:15], v[18:19], v[22:23]
	v_mul_f32_e32 v9, v10, v11
	v_cndmask_b32_e64 v11, 0, v9, s[34:35]
	v_mul_f32_e32 v9, v14, v15
	v_pk_mul_f32 v[12:13], v[112:113], v[12:13]
	v_cndmask_b32_e64 v107, 1.0, v107, s[18:19]
	v_cndmask_b32_e64 v10, 0, v9, s[26:27]
	v_cndmask_b32_e64 v9, 0, v12, s[72:73]
	v_mul_f32_e32 v12, v110, v111
	v_pk_mul_f32 v[22:23], v[108:109], v[106:107]
	v_cndmask_b32_e64 v14, 0, v13, s[70:71]
	v_cndmask_b32_e64 v13, 0, v12, s[56:57]
	v_mul_f32_e32 v12, v97, v119
	v_mov_b32_e32 v97, v23
	v_pk_mul_f32 v[24:25], v[92:93], v[96:97]
	v_mul_f32_e32 v15, v87, v121
	v_mov_b32_e32 v87, v25
	v_mul_f32_e32 v18, v210, v107
	v_pk_mul_f32 v[28:29], v[62:63], v[86:87]
	v_cndmask_b32_e64 v19, 0, v18, s[66:67]
	v_mul_f32_e32 v18, v22, v23
	v_mul_f32_e32 v22, v24, v25
	v_readlane_b32 s72, v250, 13
	v_cndmask_b32_e64 v23, 0, v22, s[58:59]
	v_mul_f32_e32 v22, v28, v29
	v_mul_f32_e32 v24, v54, v118
	s_movk_i32 s36, 0x1ff
	s_mov_b32 s40, 0x3fb8aa3b
	v_readlane_b32 s31, v250, 30
	v_readlane_b32 s30, v250, 29
	v_readlane_b32 s28, v250, 31
	v_cndmask_b32_e64 v4, 0, v4, s[22:23]
	v_cndmask_b32_e32 v6, 0, v6, vcc
	v_cndmask_b32_e64 v8, 0, v8, s[38:39]
	s_mov_b64 s[38:39], 0x2000
	v_readlane_b32 s73, v250, 14
	v_readlane_b32 s76, v250, 17
	v_readlane_b32 s77, v250, 18
	v_readlane_b32 s84, v250, 25
	v_readlane_b32 s85, v250, 26
	v_cndmask_b32_e64 v12, 0, v12, s[50:51]
	v_cndmask_b32_e64 v15, 0, v15, s[42:43]
	v_cndmask_b32_e64 v18, 0, v18, s[62:63]
	v_cndmask_b32_e64 v22, 0, v22, s[54:55]
	v_mul_f32_e32 v87, v24, v55
	s_mov_b64 s[20:21], 0
	v_readlane_b32 s74, v250, 15
	v_readlane_b32 s75, v250, 16
	v_readlane_b32 s78, v250, 19
	v_readlane_b32 s79, v250, 20
	v_readlane_b32 s80, v250, 21
	v_readlane_b32 s81, v250, 22
	v_readlane_b32 s82, v250, 23
	v_readlane_b32 s83, v250, 24
	v_readlane_b32 s86, v250, 27
	v_readlane_b32 s87, v250, 28
; template <bool MK> __device__ __forceinline__ void sb_scan(f32x16& s0, f32x16& s1, int db, int hi, float& R) {
;             f32x16 k0, k1;
; #pragma unroll
;             for (int r = 0; r < 16; ++r) {
;                 const float e0 = ex2(fminf(s0[r], 80.f)), e1 = ex2(fminf(s1[r], 80.f));
;                 const float p0 = rcp(1.0f + e0), p1 = rcp(1.0f + e1);
;                 s0[r] = e0 * p0; s1[r] = e1 * p1;
;                 k0[r] = (!MK || KKOF(0, r) < db) ? p0 : 1.0f; k1[r] = (!MK || KKOF(1, r) < db) ? p1 : 1.0f;
;             }
;             float g4[8], pg[8], E[8];
; #pragma unroll
;             for (int k4 = 0; k4 < 4; ++k4) { g4[k4] = (k0[4 * k4] * k0[4 * k4 + 1]) * (k0[4 * k4 + 2] * k0[4 * k4 + 3]); g4[4 + k4] = (k1[4 * k4] * k1[4 * k4 + 1]) * (k1[4 * k4 + 2] * k1[4 * k4 + 3]); }
; #pragma unroll
;             for (int G = 0; G < 8; ++G) pg[G] = __shfl_xor(g4[G], 32);
;             E[7] = 1.0f;
; #pragma unroll
;             for (int G = 6; G >= 0; --G) E[G] = E[G + 1] * (g4[G + 1] * pg[G + 1]);
;             const float T = E[0] * (g4[0] * pg[0]);
; #pragma unroll
;             for (int G = 0; G < 8; ++G) {
;                 const float base = R * E[G] * (hi == 0 ? pg[G] : 1.0f);
;                 const int k4 = G & 3;
;                 if (G < 4) {
;                     const float u3 = base, u2 = u3 * k0[4 * k4 + 3], u1 = u2 * k0[4 * k4 + 2], u0 = u1 * k0[4 * k4 + 1];
;                     s0[4 * k4 + 3] = (!MK || KKOF(0, 4 * k4 + 3) < db) ? s0[4 * k4 + 3] * u3 : 0.f;
;                     s0[4 * k4 + 2] = (!MK || KKOF(0, 4 * k4 + 2) < db) ? s0[4 * k4 + 2] * u2 : 0.f;
;                     s0[4 * k4 + 1] = (!MK || KKOF(0, 4 * k4 + 1) < db) ? s0[4 * k4 + 1] * u1 : 0.f;
;                     s0[4 * k4 + 0] = (!MK || KKOF(0, 4 * k4 + 0) < db) ? s0[4 * k4 + 0] * u0 : 0.f;
;                 } else {
;                     const float u3 = base, u2 = u3 * k1[4 * k4 + 3], u1 = u2 * k1[4 * k4 + 2], u0 = u1 * k1[4 * k4 + 1];
;                     s1[4 * k4 + 3] = (!MK || KKOF(1, 4 * k4 + 3) < db) ? s1[4 * k4 + 3] * u3 : 0.f;
;                     s1[4 * k4 + 2] = (!MK || KKOF(1, 4 * k4 + 2) < db) ? s1[4 * k4 + 2] * u2 : 0.f;
;                     s1[4 * k4 + 1] = (!MK || KKOF(1, 4 * k4 + 1) < db) ? s1[4 * k4 + 1] * u1 : 0.f;
;                     s1[4 * k4 + 0] = (!MK || KKOF(1, 4 * k4 + 0) < db) ? s1[4 * k4 + 0] * u0 : 0.f;
;                 }
.LBB0_603:
	s_andn2_b64 vcc, exec, s[20:21]
	s_cbranch_vccnz .LBB0_605
	v_exp_f32_e32 v16, v186
	v_exp_f32_e32 v4, v187
	v_add_f32_e32 v5, 1.0, v16
	v_rcp_f32_e32 v20, v5
	v_add_f32_e32 v6, 1.0, v4
	v_exp_f32_e32 v27, v165
	v_exp_f32_e32 v7, v164
	v_rcp_f32_e32 v8, v6
	v_exp_f32_e32 v34, v163
	v_exp_f32_e32 v36, v162
	v_add_f32_e32 v5, 1.0, v27
	v_exp_f32_e32 v45, v161
	v_rcp_f32_e32 v32, v5
	v_add_f32_e32 v5, 1.0, v7
	v_exp_f32_e32 v49, v160
	v_rcp_f32_e32 v10, v5
	v_add_f32_e32 v5, 1.0, v34
	v_exp_f32_e32 v86, v159
	v_rcp_f32_e32 v38, v5
	v_add_f32_e32 v5, 1.0, v36
	v_exp_f32_e32 v12, v158
	v_rcp_f32_e32 v9, v5
	v_add_f32_e32 v5, 1.0, v45
	v_exp_f32_e32 v91, v157
	v_rcp_f32_e32 v46, v5
	v_add_f32_e32 v5, 1.0, v49
	v_exp_f32_e32 v15, v156
	v_rcp_f32_e32 v11, v5
	v_add_f32_e32 v5, 1.0, v86
	v_exp_f32_e32 v94, v155
	v_rcp_f32_e32 v88, v5
	v_add_f32_e32 v5, 1.0, v12
	v_exp_f32_e32 v52, v154
	v_rcp_f32_e32 v22, v5
	v_add_f32_e32 v5, 1.0, v91
	v_exp_f32_e32 v97, v153
	v_rcp_f32_e32 v92, v5
	v_add_f32_e32 v5, 1.0, v15
	v_exp_f32_e32 v57, v152
	v_rcp_f32_e32 v24, v5
	v_add_f32_e32 v5, 1.0, v94
	v_exp_f32_e32 v98, v151
	v_rcp_f32_e32 v89, v5
	v_add_f32_e32 v5, 1.0, v52
	v_exp_f32_e32 v30, v150
	v_rcp_f32_e32 v23, v5
	v_add_f32_e32 v5, 1.0, v97
	v_exp_f32_e32 v103, v149
	v_rcp_f32_e32 v93, v5
	v_add_f32_e32 v5, 1.0, v57
	v_exp_f32_e32 v43, v148
	v_rcp_f32_e32 v25, v5
	v_add_f32_e32 v5, 1.0, v98
	v_exp_f32_e32 v106, v147
	v_rcp_f32_e32 v100, v5
	v_add_f32_e32 v5, 1.0, v30
	v_exp_f32_e32 v60, v146
	v_rcp_f32_e32 v18, v5
	v_add_f32_e32 v5, 1.0, v103
	v_exp_f32_e32 v109, v145
	v_rcp_f32_e32 v104, v5
	v_add_f32_e32 v5, 1.0, v43
	v_exp_f32_e32 v65, v144
	v_rcp_f32_e32 v28, v5
	v_add_f32_e32 v5, 1.0, v106
	v_exp_f32_e32 v110, v143
	v_rcp_f32_e32 v101, v5
	v_add_f32_e32 v5, 1.0, v60
	v_exp_f32_e32 v54, v142
	v_rcp_f32_e32 v50, v5
	v_add_f32_e32 v5, 1.0, v109
	v_exp_f32_e32 v115, v141
	v_rcp_f32_e32 v105, v5
	v_add_f32_e32 v5, 1.0, v65
	v_exp_f32_e32 v59, v140
	v_rcp_f32_e32 v62, v5
	v_add_f32_e32 v5, 1.0, v110
	v_exp_f32_e32 v6, v139
	v_rcp_f32_e32 v112, v5
	v_add_f32_e32 v5, 1.0, v54
	v_exp_f32_e32 v13, v138
	v_rcp_f32_e32 v19, v5
	v_add_f32_e32 v5, 1.0, v115
	v_exp_f32_e32 v120, v137
	v_rcp_f32_e32 v116, v5
	v_add_f32_e32 v5, 1.0, v59
	v_exp_f32_e32 v67, v136
	v_rcp_f32_e32 v29, v5
	v_add_f32_e32 v5, 1.0, v6
	v_rcp_f32_e32 v118, v5
	v_add_f32_e32 v5, 1.0, v13
	v_rcp_f32_e32 v51, v5
	v_add_f32_e32 v5, 1.0, v120
	v_rcp_f32_e32 v122, v5
	v_add_f32_e32 v5, 1.0, v67
	v_rcp_f32_e32 v63, v5
	v_pk_mul_f32 v[130:131], v[18:19], v[28:29]
	v_pk_mul_f32 v[128:129], v[22:23], v[24:25]
	v_pk_mul_f32 v[124:125], v[8:9], v[10:11]
	v_pk_mul_f32 v[132:133], v[50:51], v[62:63]
	v_mul_f32_e32 v5, v128, v129
	v_pk_mul_f32 v[130:131], v[130:131], v[132:133]
	ds_bpermute_b32 v132, v201, v130
	ds_bpermute_b32 v133, v201, v131
	v_pk_mul_f32 v[124:125], v[124:125], v[124:125] op_sel:[0,1] op_sel_hi:[1,0]
	ds_bpermute_b32 v14, v201, v5
	ds_bpermute_b32 v117, v201, v124
	v_mov_b32_e32 v113, v124
	s_waitcnt lgkmcnt(2)
	v_pk_mul_f32 v[130:131], v[130:131], v[132:133]
	v_pk_mul_f32 v[128:129], v[100:101], v[104:105]
	v_pk_mul_f32 v[136:137], v[130:131], v[130:131] op_sel:[0,1] op_sel_hi:[1,0]
	s_waitcnt lgkmcnt(1)
	v_mul_f32_e32 v119, v5, v14
	v_mov_b32_e32 v123, v136
	v_pk_mul_f32 v[138:139], v[118:119], v[122:123]
	s_waitcnt lgkmcnt(0)
	v_pk_mul_f32 v[124:125], v[112:113], v[116:117]
	v_pk_mul_f32 v[126:127], v[88:89], v[92:93]
	v_pk_mul_f32 v[124:125], v[124:125], v[138:139]
	ds_bpermute_b32 v5, v201, v124
	v_mul_f32_e32 v17, v128, v129
	ds_bpermute_b32 v31, v201, v17
	v_pk_mul_f32 v[126:127], v[126:127], v[126:127] op_sel:[0,1] op_sel_hi:[1,0]
	ds_bpermute_b32 v33, v201, v126
	s_waitcnt lgkmcnt(2)
	v_mul_f32_e32 v21, v124, v5
	v_mul_f32_e32 v47, v21, v125
	s_waitcnt lgkmcnt(1)
	v_mul_f32_e32 v39, v17, v31
	v_mov_b32_e32 v21, v126
	v_pk_mul_f32 v[128:129], v[38:39], v[46:47]
	s_waitcnt lgkmcnt(0)
; template <bool MK> __device__ __forceinline__ void sb_scan(f32x16& s0, f32x16& s1, int db, int hi, float& R) {
;     ...
;             float g4[8], pg[8], E[8];
; #pragma unroll
;             for (int k4 = 0; k4 < 4; ++k4) { g4[k4] = (k0[4 * k4] * k0[4 * k4 + 1]) * (k0[4 * k4 + 2] * k0[4 * k4 + 3]); g4[4 + k4] = (k1[4 * k4] * k1[4 * k4 + 1]) * (k1[4 * k4 + 2] * k1[4 * k4 + 3]); }
; #pragma unroll
;             for (int G = 0; G < 8; ++G) pg[G] = __shfl_xor(g4[G], 32);
;             E[7] = 1.0f;
; #pragma unroll
;             for (int G = 6; G >= 0; --G) E[G] = E[G + 1] * (g4[G + 1] * pg[G + 1]);
;             const float T = E[0] * (g4[0] * pg[0]);
; #pragma unroll
;             for (int G = 0; G < 8; ++G) {
;                 const float base = R * E[G] * (hi == 0 ? pg[G] : 1.0f);
;                 const int k4 = G & 3;
;                 if (G < 4) {
;                     const float u3 = base, u2 = u3 * k0[4 * k4 + 3], u1 = u2 * k0[4 * k4 + 2], u0 = u1 * k0[4 * k4 + 1];
;                     s0[4 * k4 + 3] = (!MK || KKOF(0, 4 * k4 + 3) < db) ? s0[4 * k4 + 3] * u3 : 0.f;
;                     s0[4 * k4 + 2] = (!MK || KKOF(0, 4 * k4 + 2) < db) ? s0[4 * k4 + 2] * u2 : 0.f;
;                     s0[4 * k4 + 1] = (!MK || KKOF(0, 4 * k4 + 1) < db) ? s0[4 * k4 + 1] * u1 : 0.f;
;                     s0[4 * k4 + 0] = (!MK || KKOF(0, 4 * k4 + 0) < db) ? s0[4 * k4 + 0] * u0 : 0.f;
;                 } else {
;                     const float u3 = base, u2 = u3 * k1[4 * k4 + 3], u1 = u2 * k1[4 * k4 + 2], u0 = u1 * k1[4 * k4 + 1];
;                     s1[4 * k4 + 3] = (!MK || KKOF(1, 4 * k4 + 3) < db) ? s1[4 * k4 + 3] * u3 : 0.f;
;                     s1[4 * k4 + 2] = (!MK || KKOF(1, 4 * k4 + 2) < db) ? s1[4 * k4 + 2] * u2 : 0.f;
;                     s1[4 * k4 + 1] = (!MK || KKOF(1, 4 * k4 + 1) < db) ? s1[4 * k4 + 1] * u1 : 0.f;
;                     s1[4 * k4 + 0] = (!MK || KKOF(1, 4 * k4 + 0) < db) ? s1[4 * k4 + 0] * u0 : 0.f;
;                 }
;             }
	v_pk_mul_f32 v[126:127], v[20:21], v[32:33]
	v_cndmask_b32_e64 v95, 1.0, v33, s[18:19]
	v_pk_mul_f32 v[126:127], v[126:127], v[128:129]
	ds_bpermute_b32 v119, v201, v126
	v_mov_b32_e32 v39, v127
	v_mov_b32_e32 v128, v89
	v_mov_b32_e32 v17, v38
	v_mul_f32_e32 v124, v6, v118
	s_waitcnt lgkmcnt(0)
	v_cndmask_b32_e64 v35, 1.0, v119, s[18:19]
	v_pk_mul_f32 v[34:35], v[34:35], v[38:39]
	v_pk_mul_f32 v[38:39], v[94:95], v[128:129]
	v_mov_b32_e32 v44, v35
	v_pk_mul_f32 v[44:45], v[46:47], v[44:45] op_sel_hi:[0,1]
	v_mov_b32_e32 v21, v44
	v_mov_b32_e32 v6, v93
	v_mov_b32_e32 v96, v39
	v_pk_mul_f32 v[16:17], v[16:17], v[20:21]
	v_pk_mul_f32 v[94:95], v[6:7], v[96:97] op_sel_hi:[0,1]
	v_mov_b32_e32 v26, v17
	v_mov_b32_e32 v87, v89
	v_mov_b32_e32 v89, v94
	v_cndmask_b32_e64 v107, 1.0, v31, s[18:19]
	v_mov_b32_e32 v46, v101
	v_pk_mul_f32 v[20:21], v[32:33], v[26:27] op_sel_hi:[0,1]
	v_pk_mul_f32 v[26:27], v[86:87], v[88:89]
	v_pk_mul_f32 v[88:89], v[106:107], v[46:47]
	v_cndmask_b32_e64 v37, 1.0, v117, s[18:19]
	v_mov_b32_e32 v138, v9
	v_mov_b32_e32 v90, v27
	v_mov_b32_e32 v6, v105
	v_mov_b32_e32 v108, v89
	v_pk_mul_f32 v[36:37], v[36:37], v[138:139]
	v_pk_mul_f32 v[86:87], v[92:93], v[90:91] op_sel_hi:[0,1]
	v_pk_mul_f32 v[90:91], v[6:7], v[108:109] op_sel_hi:[0,1]
	v_mov_b32_e32 v6, v11
	v_mov_b32_e32 v48, v37
	v_pk_mul_f32 v[48:49], v[6:7], v[48:49] op_sel_hi:[0,1]
	v_cndmask_b32_e64 v121, 1.0, v5, s[18:19]
	v_mov_b32_e32 v5, v9
	v_mov_b32_e32 v9, v48
	v_pk_mul_f32 v[4:5], v[4:5], v[8:9]
	v_cndmask_b32_e64 v53, 1.0, v14, s[18:19]
	v_mov_b32_e32 v8, v23
	v_mov_b32_e32 v9, v136
	v_mov_b32_e32 v6, v5
	v_pk_mul_f32 v[8:9], v[52:53], v[8:9]
	v_pk_mul_f32 v[6:7], v[10:11], v[6:7] op_sel_hi:[0,1]
	v_mov_b32_e32 v10, v25
	v_mov_b32_e32 v56, v9
	v_pk_mul_f32 v[52:53], v[10:11], v[56:57] op_sel_hi:[0,1]
	v_mul_f32_e32 v140, v13, v51
	v_mov_b32_e32 v13, v23
	v_mov_b32_e32 v23, v52
	v_cndmask_b32_e64 v61, 1.0, v132, s[18:19]
	v_mov_b32_e32 v130, v50
	v_pk_mul_f32 v[10:11], v[12:13], v[22:23]
	v_pk_mul_f32 v[22:23], v[60:61], v[130:131]
	v_mov_b32_e32 v14, v11
	v_mov_b32_e32 v64, v23
	v_pk_mul_f32 v[12:13], v[24:25], v[14:15] op_sel_hi:[0,1]
	v_pk_mul_f32 v[24:25], v[62:63], v[64:65] op_sel_hi:[0,1]
	v_mov_b32_e32 v31, v50
	v_mov_b32_e32 v14, v18
	v_mov_b32_e32 v15, v24
	v_mov_b32_e32 v123, v125
	v_pk_mul_f32 v[14:15], v[30:31], v[14:15]
	v_pk_mul_f32 v[32:33], v[120:121], v[122:123]
	v_mov_b32_e32 v42, v15
	v_cndmask_b32_e64 v66, 1.0, v133, s[18:19]
	v_mov_b32_e32 v18, v63
	v_mul_f32_e32 v96, v122, v33
	v_pk_mul_f32 v[30:31], v[28:29], v[42:43] op_sel_hi:[0,1]
	v_pk_mul_f32 v[42:43], v[18:19], v[66:67] op_sel_hi:[0,1]
	v_mov_b32_e32 v99, v101
	v_mov_b32_e32 v101, v90
	v_mov_b32_e32 v111, v118
	v_mov_b32_e32 v113, v96
	v_mov_b32_e32 v55, v51
	v_mov_b32_e32 v18, v19
	v_mov_b32_e32 v19, v42
	v_pk_mul_f32 v[46:47], v[98:99], v[100:101]
	v_pk_mul_f32 v[98:99], v[110:111], v[112:113]
	v_pk_mul_f32 v[18:19], v[54:55], v[18:19]
	v_mov_b32_e32 v102, v47
	v_mov_b32_e32 v114, v99
	v_mov_b32_e32 v28, v29
	v_mov_b32_e32 v58, v19
	v_pk_mul_f32 v[92:93], v[104:105], v[102:103] op_sel_hi:[0,1]
	v_mov_b32_e32 v125, v32
	v_mov_b32_e32 v97, v33
	v_pk_mul_f32 v[100:101], v[116:117], v[114:115] op_sel_hi:[0,1]
	v_mov_b32_e32 v141, v66
	v_pk_mul_f32 v[28:29], v[28:29], v[58:59] op_sel_hi:[0,1]
	v_pk_mul_f32 v[10:11], v[12:13], v[10:11]
	v_pk_mul_f32 v[12:13], v[24:25], v[22:23]
	v_mul_f32_e32 v24, v126, v119
	v_pk_mul_f32 v[32:33], v[20:21], v[16:17]
	v_pk_mul_f32 v[16:17], v[44:45], v[34:35]
	v_pk_mul_f32 v[26:27], v[86:87], v[26:27]
	v_pk_mul_f32 v[20:21], v[94:95], v[38:39]
	v_pk_mul_f32 v[46:47], v[92:93], v[46:47]
	v_pk_mul_f32 v[34:35], v[90:91], v[88:89]
	v_pk_mul_f32 v[38:39], v[100:101], v[98:99]
	v_pk_mul_f32 v[44:45], v[124:125], v[96:97]
	v_pk_mul_f32 v[6:7], v[6:7], v[4:5]
	v_pk_mul_f32 v[4:5], v[48:49], v[36:37]
	v_pk_mul_f32 v[8:9], v[52:53], v[8:9]
	v_pk_mul_f32 v[14:15], v[30:31], v[14:15]
	v_pk_mul_f32 v[22:23], v[28:29], v[18:19]
	v_pk_mul_f32 v[18:19], v[42:43], v[140:141]
	v_mul_f32_e32 v87, v24, v127

; #define LAS __attribute__((address_space(3)))
; __device__ __forceinline__ float ex2(float x) { return __builtin_amdgcn_exp2f(x); }
; __device__ __forceinline__ float rcp(float x) { return __builtin_amdgcn_rcpf(x); }
; template <bool MK> __device__ __forceinline__ void sb_scan(f32x16& s0, f32x16& s1, int db, int hi, float& R) {
;             f32x16 k0, k1;
; #pragma unroll
;             for (int r = 0; r < 16; ++r) {
;                 const float e0 = ex2(fminf(s0[r], 80.f)), e1 = ex2(fminf(s1[r], 80.f));
;                 const float p0 = rcp(1.0f + e0), p1 = rcp(1.0f + e1);
;                 s0[r] = e0 * p0; s1[r] = e1 * p1;
;                 k0[r] = (!MK || KKOF(0, r) < db) ? p0 : 1.0f; k1[r] = (!MK || KKOF(1, r) < db) ? p1 : 1.0f;
;             }
; __device__ __forceinline__ void sb_unit(const Params& p, LAS unsigned char* lds, int b, int hp, int qb, int tid, int lane, int wave) {
;     ...
;         if (!dead && 64 * j < tmaxw) {
;             const LAS unsigned char* stg = lds + (it & 3) * (2 * STG_BYTES) + hsel * STG_BYTES;
;             f32x16 s0, s1;
;             qk_tile(stg, qf, col, hi, s0, s1, 0.f);
;             const int db = t - 64 * j - 4 * hi;
;             if (64 * j + 63 < tmaxw - 31) sb_scan<false>(s0, s1, db, hi, R); else sb_scan<true>(s0, s1, db, hi, R);
.LBB0_622:
	s_xor_b64 s[4:5], s[24:25], -1
	s_andn2_b64 vcc, exec, s[4:5]
	s_mov_b64 s[24:25], -1
	s_cbranch_vccnz .LBB0_629
	s_sub_i32 s4, s90, 63
	s_cmp_ge_i32 s4, s91
	s_mov_b64 s[24:25], 0
	s_cbranch_scc1 .LBB0_629
	s_add_i32 s4, s9, 0xfffe8000
	s_and_b32 s4, s4, 0x18000
	s_add_i32 s4, s31, s4
	v_add_u32_e32 v86, s4, v176
	v_add_u32_e32 v52, v86, v178
	ds_read_b128 v[36:39], v52
	v_add_u32_e32 v96, v86, v179
	ds_read_b128 v[92:95], v96
	ds_read_b128 v[52:55], v52 offset:4096
	s_mov_b64 s[24:25], -1
	s_cmp_ge_i32 s90, s28
	s_waitcnt lgkmcnt(2)
	v_mfma_f32_32x32x16_bf16 v[36:51], v[36:39], v[68:71], 0
	s_waitcnt lgkmcnt(1)
	v_mfma_f32_32x32x16_bf16 v[36:51], v[92:95], v[72:75], v[36:51]
	ds_read_b128 v[92:95], v96 offset:4096
	v_add_u32_e32 v96, v86, v180
	v_add_u32_e32 v86, v86, v181
	s_waitcnt lgkmcnt(1)
	v_mfma_f32_32x32x16_bf16 v[52:67], v[52:55], v[68:71], 0
	s_waitcnt lgkmcnt(0)
	v_mfma_f32_32x32x16_bf16 v[52:67], v[92:95], v[72:75], v[52:67]
	ds_read_b128 v[92:95], v96
	s_waitcnt lgkmcnt(0)
	v_mfma_f32_32x32x16_bf16 v[36:51], v[92:95], v[76:79], v[36:51]
	ds_read_b128 v[92:95], v96 offset:4096
	s_waitcnt lgkmcnt(0)
	v_mfma_f32_32x32x16_bf16 v[52:67], v[92:95], v[76:79], v[52:67]
	ds_read_b128 v[92:95], v86
	s_waitcnt lgkmcnt(0)
	v_mfma_f32_32x32x16_bf16 v[36:51], v[92:95], v[80:83], v[36:51]
	ds_read_b128 v[92:95], v86 offset:4096
	s_waitcnt lgkmcnt(0)
	v_mfma_f32_32x32x16_bf16 v[52:67], v[92:95], v[80:83], v[52:67]
	s_nop 8
	v_min_f32_e32 v232, 0x42a00000, v36
	v_min_f32_e32 v231, 0x42a00000, v37
	v_min_f32_e32 v229, 0x42a00000, v38
	v_min_f32_e32 v227, 0x42a00000, v39
	v_min_f32_e32 v225, 0x42a00000, v40
	v_min_f32_e32 v223, 0x42a00000, v41
	v_min_f32_e32 v221, 0x42a00000, v42
	v_min_f32_e32 v233, 0x42a00000, v52
	v_min_f32_e32 v230, 0x42a00000, v53
	v_min_f32_e32 v228, 0x42a00000, v54
	v_min_f32_e32 v226, 0x42a00000, v55
	v_min_f32_e32 v224, 0x42a00000, v56
	v_min_f32_e32 v222, 0x42a00000, v57
	v_min_f32_e32 v220, 0x42a00000, v58
	v_min_f32_e32 v219, 0x42a00000, v43
	v_min_f32_e32 v217, 0x42a00000, v59
	v_min_f32_e32 v216, 0x42a00000, v44
	v_min_f32_e32 v215, 0x42a00000, v60
	v_min_f32_e32 v214, 0x42a00000, v45
	v_min_f32_e32 v213, 0x42a00000, v61
	v_min_f32_e32 v212, 0x42a00000, v46
	v_min_f32_e32 v211, 0x42a00000, v62
	v_min_f32_e32 v210, 0x42a00000, v47
	v_min_f32_e32 v209, 0x42a00000, v63
	v_min_f32_e32 v208, 0x42a00000, v48
	v_min_f32_e32 v207, 0x42a00000, v64
	v_min_f32_e32 v206, 0x42a00000, v49
	v_min_f32_e32 v205, 0x42a00000, v65
	v_min_f32_e32 v204, 0x42a00000, v50
	v_min_f32_e32 v203, 0x42a00000, v66
	v_min_f32_e32 v202, 0x42a00000, v51
	v_min_f32_e32 v187, 0x42a00000, v67
	s_cbranch_scc0 .LBB0_626
	v_exp_f32_e32 v116, v214
	v_exp_f32_e32 v55, v213
	v_cmp_lt_i32_e64 s[54:55], 50, v186
	v_add_f32_e32 v57, 1.0, v116
	v_rcp_f32_e32 v118, v57
	v_add_f32_e32 v57, 1.0, v55
	v_rcp_f32_e32 v59, v57
	v_cmp_lt_i32_e64 s[60:61], 51, v186
	v_exp_f32_e32 v140, v205
	v_mul_f32_e32 v137, v55, v59
	v_exp_f32_e32 v124, v212
	v_exp_f32_e32 v55, v211
	v_add_f32_e32 v57, 1.0, v124
	v_rcp_f32_e32 v138, v57
	v_add_f32_e32 v57, 1.0, v55
	v_rcp_f32_e32 v57, v57
	v_exp_f32_e32 v62, v222
	v_exp_f32_e32 v94, v229
	v_mul_f32_e32 v143, v55, v57
	v_exp_f32_e32 v158, v210
	v_exp_f32_e32 v55, v209
	v_cndmask_b32_e64 v128, 1.0, v57, s[54:55]
	v_add_f32_e32 v57, 1.0, v158
	v_rcp_f32_e32 v164, v57
	v_add_f32_e32 v57, 1.0, v55
	v_rcp_f32_e32 v57, v57
	v_exp_f32_e32 v48, v228
	v_mul_f32_e32 v147, v55, v57
	v_cndmask_b32_e64 v134, 1.0, v57, s[60:61]
	v_exp_f32_e32 v57, v206
	v_add_f32_e32 v51, 1.0, v62
	v_exp_f32_e32 v42, v232
	v_add_f32_e32 v61, 1.0, v57
	v_rcp_f32_e32 v61, v61
	v_rcp_f32_e32 v92, v51
	v_add_f32_e32 v65, 1.0, v140
	v_mul_f32_e32 v93, v57, v61
	v_exp_f32_e32 v57, v204
	v_exp_f32_e32 v36, v233
	v_exp_f32_e32 v110, v221
	v_rcp_f32_e32 v142, v65
	v_add_f32_e32 v39, 1.0, v94
	v_exp_f32_e32 v96, v220
	v_exp_f32_e32 v144, v203
	v_add_f32_e32 v65, 1.0, v57
	v_rcp_f32_e32 v98, v39
	v_add_f32_e32 v39, 1.0, v48
	v_rcp_f32_e32 v65, v65
	v_add_f32_e32 v37, 1.0, v42
	v_rcp_f32_e32 v50, v39
	v_rcp_f32_e32 v44, v37
	v_add_f32_e32 v37, 1.0, v36
	v_exp_f32_e32 v132, v227
	v_add_f32_e32 v51, 1.0, v110
	v_rcp_f32_e32 v38, v37
	v_exp_f32_e32 v56, v226
	v_rcp_f32_e32 v112, v51
	v_add_f32_e32 v51, 1.0, v96
	v_exp_f32_e32 v58, v231
	v_rcp_f32_e32 v102, v51
	v_mul_f32_e32 v103, v57, v65
	v_exp_f32_e32 v40, v230
	v_exp_f32_e32 v120, v219
	v_exp_f32_e32 v159, v208
	v_exp_f32_e32 v234, v202
	v_add_f32_e32 v39, 1.0, v132
	v_exp_f32_e32 v152, v217
	v_exp_f32_e32 v130, v207
	v_exp_f32_e32 v148, v187
	v_rcp_f32_e32 v126, v39
	v_add_f32_e32 v39, 1.0, v56
	v_add_f32_e32 v37, 1.0, v58
	v_rcp_f32_e32 v60, v39
	v_rcp_f32_e32 v64, v37
	v_add_f32_e32 v37, 1.0, v40
	v_exp_f32_e32 v133, v225
	v_add_f32_e32 v51, 1.0, v120
	v_add_f32_e32 v55, 1.0, v159
	v_add_f32_e32 v57, 1.0, v234
	v_rcp_f32_e32 v46, v37
	v_exp_f32_e32 v52, v224
	v_rcp_f32_e32 v122, v51
	v_add_f32_e32 v51, 1.0, v152
	v_rcp_f32_e32 v165, v55
	v_add_f32_e32 v55, 1.0, v130
	v_add_f32_e32 v67, 1.0, v144
	v_rcp_f32_e32 v236, v57
	v_add_f32_e32 v57, 1.0, v148
	v_rcp_f32_e32 v154, v51
	v_rcp_f32_e32 v136, v55
	v_rcp_f32_e32 v146, v67
	v_rcp_f32_e32 v150, v57
	v_exp_f32_e32 v106, v216
	v_cmp_lt_i32_e32 vcc, 32, v186
	v_cmp_lt_i32_e64 s[26:27], 33, v186
	v_cmp_lt_i32_e64 s[28:29], 34, v186
	v_cmp_lt_i32_e64 s[34:35], 35, v186
	v_add_f32_e32 v39, 1.0, v133
	v_exp_f32_e32 v153, v215
	v_cndmask_b32_e32 v43, 1.0, v38, vcc
	v_cndmask_b32_e64 v37, 1.0, v46, s[26:27]
	v_cndmask_b32_e64 v41, 1.0, v50, s[28:29]
	v_cndmask_b32_e64 v49, 1.0, v60, s[34:35]
	v_rcp_f32_e32 v127, v39
	v_add_f32_e32 v39, 1.0, v52
; __device__ __forceinline__ float ex2(float x) { return __builtin_amdgcn_exp2f(x); }
; __device__ __forceinline__ float rcp(float x) { return __builtin_amdgcn_rcpf(x); }
; template <bool MK> __device__ __forceinline__ void sb_scan(f32x16& s0, f32x16& s1, int db, int hi, float& R) {
;             f32x16 k0, k1;
; #pragma unroll
;             for (int r = 0; r < 16; ++r) {
;                 const float e0 = ex2(fminf(s0[r], 80.f)), e1 = ex2(fminf(s1[r], 80.f));
;                 const float p0 = rcp(1.0f + e0), p1 = rcp(1.0f + e1);
;                 s0[r] = e0 * p0; s1[r] = e1 * p1;
;                 k0[r] = (!MK || KKOF(0, r) < db) ? p0 : 1.0f; k1[r] = (!MK || KKOF(1, r) < db) ? p1 : 1.0f;
;             }
;             float g4[8], pg[8], E[8];
; #pragma unroll
;             for (int k4 = 0; k4 < 4; ++k4) { g4[k4] = (k0[4 * k4] * k0[4 * k4 + 1]) * (k0[4 * k4 + 2] * k0[4 * k4 + 3]); g4[4 + k4] = (k1[4 * k4] * k1[4 * k4 + 1]) * (k1[4 * k4 + 2] * k1[4 * k4 + 3]); }
; #pragma unroll
;             for (int G = 0; G < 8; ++G) pg[G] = __shfl_xor(g4[G], 32);
;             E[7] = 1.0f;
; #pragma unroll
;             for (int G = 6; G >= 0; --G) E[G] = E[G + 1] * (g4[G + 1] * pg[G + 1]);
;             const float T = E[0] * (g4[0] * pg[0]);
	v_cmp_lt_i32_e64 s[58:59], 56, v186
	v_cmp_lt_i32_e64 s[64:65], 57, v186
	v_cmp_lt_i32_e64 s[66:67], 58, v186
	v_cmp_lt_i32_e64 s[68:69], 59, v186
	v_rcp_f32_e32 v54, v39
	v_cndmask_b32_e64 v55, 1.0, v136, s[58:59]
	v_cndmask_b32_e64 v131, 1.0, v142, s[64:65]
	v_cndmask_b32_e64 v141, 1.0, v146, s[66:67]
	v_cndmask_b32_e64 v145, 1.0, v150, s[68:69]
	v_mul_f32_e32 v43, v43, v37
	v_mul_f32_e32 v57, v41, v49
	v_add_f32_e32 v51, 1.0, v106
	v_mul_f32_e32 v241, v43, v57
	v_mul_f32_e32 v55, v55, v131
	v_mul_f32_e32 v57, v141, v145
	v_rcp_f32_e32 v108, v51
	v_add_f32_e32 v51, 1.0, v153
	v_mul_f32_e32 v129, v55, v57
	v_cmp_lt_i32_e64 s[30:31], 40, v186
	v_exp_f32_e32 v39, v223
	v_cmp_lt_i32_e64 s[38:39], 41, v186
	v_cmp_lt_i32_e64 s[42:43], 42, v186
	v_rcp_f32_e32 v155, v51
	ds_bpermute_b32 v135, v201, v129
	v_cmp_lt_i32_e64 s[74:75], 43, v186
	v_cndmask_b32_e64 v45, 1.0, v54, s[30:31]
	v_cndmask_b32_e64 v53, 1.0, v92, s[38:39]
	v_cndmask_b32_e64 v63, 1.0, v102, s[42:43]
	v_cmp_lt_i32_e64 s[76:77], 26, v186
	v_cndmask_b32_e64 v97, 1.0, v154, s[74:75]
	v_mul_f32_e32 v45, v45, v53
	v_cndmask_b32_e64 v160, 1.0, v65, s[76:77]
	v_mul_f32_e32 v65, v63, v97
	v_cmp_lt_i32_e64 s[46:47], 49, v186
	v_cmp_lt_i32_e64 s[72:73], 48, v186
	v_mul_f32_e32 v45, v45, v65
	v_add_f32_e32 v47, 1.0, v39
	v_cndmask_b32_e64 v55, 1.0, v155, s[72:73]
	ds_bpermute_b32 v65, v201, v45
	v_cndmask_b32_e64 v163, 1.0, v59, s[46:47]
	v_rcp_f32_e32 v47, v47
	v_mul_f32_e32 v86, v55, v163
	s_waitcnt lgkmcnt(1)
	v_pk_mul_f32 v[156:157], v[128:129], v[134:135]
	v_pk_mul_f32 v[152:153], v[152:153], v[154:155]
	v_pk_mul_f32 v[154:155], v[86:87], v[156:157]
	ds_bpermute_b32 v244, v201, v154
	v_cmp_lt_i32_e64 s[44:45], 9, v186
	v_cmp_lt_i32_e64 s[48:49], 10, v186
	v_cmp_lt_i32_e64 s[52:53], 11, v186
	v_cmp_lt_i32_e64 s[82:83], 8, v186
	v_cndmask_b32_e64 v115, 1.0, v112, s[48:49]
	v_cndmask_b32_e64 v111, 1.0, v122, s[52:53]
	v_cmp_lt_i32_e64 s[50:51], 16, v186
	v_cmp_lt_i32_e64 s[56:57], 17, v186
	v_cmp_lt_i32_e64 s[62:63], 18, v186
	s_waitcnt lgkmcnt(1)
	v_mul_f32_e32 v161, v45, v65
	v_pk_mul_f32 v[132:133], v[132:133], v[126:127]
	v_cndmask_b32_e64 v45, 1.0, v127, s[82:83]
	v_cndmask_b32_e64 v127, 1.0, v47, s[44:45]
	v_cmp_lt_i32_e64 s[86:87], 19, v186
	v_cndmask_b32_e64 v51, 1.0, v108, s[50:51]
	v_cndmask_b32_e64 v107, 1.0, v118, s[56:57]
	v_cndmask_b32_e64 v117, 1.0, v138, s[62:63]
	v_mul_f32_e32 v43, v115, v111
	v_mul_f32_e32 v45, v45, v127
	v_cndmask_b32_e64 v125, 1.0, v164, s[86:87]
	v_mul_f32_e32 v51, v51, v107
	ds_bpermute_b32 v243, v201, v241
	v_mul_f32_e32 v105, v45, v43
	v_mul_f32_e32 v43, v117, v125
	s_waitcnt lgkmcnt(1)
	v_cndmask_b32_e64 v245, 1.0, v244, s[18:19]
	v_mul_f32_e32 v43, v51, v43
	v_cmp_lt_i32_e64 s[70:71], 25, v186
	v_pk_mul_f32 v[154:155], v[154:155], v[244:245]
	v_pk_mov_b32 v[156:157], v[156:157], v[134:135] op_sel:[1,0]
	v_cmp_lt_i32_e64 s[80:81], 24, v186
	ds_bpermute_b32 v45, v201, v43
	v_cmp_lt_i32_e64 s[78:79], 27, v186
	v_pk_mul_f32 v[156:157], v[156:157], v[154:155]
	v_pk_mul_f32 v[158:159], v[158:159], v[164:165]
	v_cndmask_b32_e64 v240, 1.0, v165, s[80:81]
	v_cndmask_b32_e64 v165, 1.0, v61, s[70:71]
	v_cndmask_b32_e64 v238, 1.0, v236, s[78:79]
	v_mov_b32_e32 v239, v156
	v_mov_b32_e32 v242, v165
	v_pk_mul_f32 v[244:245], v[160:161], v[238:239]
	s_waitcnt lgkmcnt(1)
	v_pk_mul_f32 v[240:241], v[240:241], v[242:243]
	s_waitcnt lgkmcnt(0)
	v_mul_f32_e32 v101, v43, v45
	v_pk_mul_f32 v[240:241], v[240:241], v[244:245]
	ds_bpermute_b32 v43, v201, v240
	ds_bpermute_b32 v67, v201, v105
	v_mul_f32_e32 v237, v87, v241
	v_cndmask_b32_e64 v57, 1.0, v243, s[18:19]
	v_mov_b32_e32 v243, v238
	s_waitcnt lgkmcnt(1)
	v_cndmask_b32_e64 v235, 1.0, v43, s[18:19]
	v_pk_mul_f32 v[234:235], v[234:235], v[236:237]
	v_mul_f32_e32 v242, v240, v43
	v_mov_b32_e32 v236, v241
	v_mov_b32_e32 v237, v235
	v_cmp_lt_i32_e64 s[24:25], 0, v186
	v_cmp_lt_i32_e64 s[36:37], 1, v186
	v_cmp_lt_i32_e64 s[40:41], 2, v186
	v_cmp_lt_i32_e64 s[84:85], 3, v186
	v_pk_mul_f32 v[236:237], v[242:243], v[236:237]
	v_cndmask_b32_e64 v104, 1.0, v44, s[24:25]
	v_cndmask_b32_e64 v66, 1.0, v64, s[36:37]
	v_cndmask_b32_e64 v100, 1.0, v98, s[40:41]
	v_cndmask_b32_e64 v246, 1.0, v126, s[84:85]
	v_mov_b32_e32 v247, v236
	s_waitcnt lgkmcnt(0)
	v_pk_mul_f32 v[104:105], v[104:105], v[66:67]
	v_pk_mul_f32 v[238:239], v[100:101], v[246:247]
	v_cndmask_b32_e64 v121, 1.0, v67, s[18:19]
	v_pk_mul_f32 v[104:105], v[104:105], v[238:239]
	ds_bpermute_b32 v129, v201, v104
	v_mul_f32_e32 v123, v87, v239
	v_pk_mul_f32 v[120:121], v[120:121], v[122:123]
	v_mov_b32_e32 v114, v87
	v_mov_b32_e32 v113, v121
	v_pk_mul_f32 v[110:111], v[110:111], v[112:113]
	v_mov_b32_e32 v112, v105
	v_mov_b32_e32 v113, v111
	s_waitcnt lgkmcnt(0)
; template <bool MK> __device__ __forceinline__ void sb_scan(f32x16& s0, f32x16& s1, int db, int hi, float& R) {
;     ...
;             for (int G = 0; G < 8; ++G) pg[G] = __shfl_xor(g4[G], 32);
;             E[7] = 1.0f;
; #pragma unroll
;             for (int G = 6; G >= 0; --G) E[G] = E[G + 1] * (g4[G + 1] * pg[G + 1]);
;             const float T = E[0] * (g4[0] * pg[0]);
; #pragma unroll
;             for (int G = 0; G < 8; ++G) {
;                 const float base = R * E[G] * (hi == 0 ? pg[G] : 1.0f);
;                 const int k4 = G & 3;
;                 if (G < 4) {
;                     const float u3 = base, u2 = u3 * k0[4 * k4 + 3], u1 = u2 * k0[4 * k4 + 2], u0 = u1 * k0[4 * k4 + 1];
;                     s0[4 * k4 + 3] = (!MK || KKOF(0, 4 * k4 + 3) < db) ? s0[4 * k4 + 3] * u3 : 0.f;
;                     s0[4 * k4 + 2] = (!MK || KKOF(0, 4 * k4 + 2) < db) ? s0[4 * k4 + 2] * u2 : 0.f;
;                     s0[4 * k4 + 1] = (!MK || KKOF(0, 4 * k4 + 1) < db) ? s0[4 * k4 + 1] * u1 : 0.f;
;                     s0[4 * k4 + 0] = (!MK || KKOF(0, 4 * k4 + 0) < db) ? s0[4 * k4 + 0] * u0 : 0.f;
;                 } else {
;                     const float u3 = base, u2 = u3 * k1[4 * k4 + 3], u1 = u2 * k1[4 * k4 + 2], u0 = u1 * k1[4 * k4 + 1];
;                     s1[4 * k4 + 3] = (!MK || KKOF(1, 4 * k4 + 3) < db) ? s1[4 * k4 + 3] * u3 : 0.f;
;                     s1[4 * k4 + 2] = (!MK || KKOF(1, 4 * k4 + 2) < db) ? s1[4 * k4 + 2] * u2 : 0.f;
;                     s1[4 * k4 + 1] = (!MK || KKOF(1, 4 * k4 + 1) < db) ? s1[4 * k4 + 1] * u1 : 0.f;
;                     s1[4 * k4 + 0] = (!MK || KKOF(1, 4 * k4 + 0) < db) ? s1[4 * k4 + 0] * u0 : 0.f;
;                 }
;             }
;             R *= T;
	v_cndmask_b32_e64 v126, 1.0, v129, s[18:19]
	v_pk_mul_f32 v[112:113], v[114:115], v[112:113]
	v_mov_b32_e32 v95, v246
	v_pk_mul_f32 v[114:115], v[126:127], v[112:113]
	v_cndmask_b32_e64 v162, 1.0, v65, s[18:19]
	v_mov_b32_e32 v99, v114
	v_pk_mul_f32 v[94:95], v[94:95], v[98:99]
	v_mov_b32_e32 v59, v100
	v_mov_b32_e32 v65, v95
	v_pk_mul_f32 v[58:59], v[58:59], v[64:65]
	v_mov_b32_e32 v43, v66
	v_mov_b32_e32 v66, v87
	v_mov_b32_e32 v67, v160
	v_cndmask_b32_e64 v164, 1.0, v45, s[18:19]
	v_mov_b32_e32 v45, v59
	v_pk_mul_f32 v[98:99], v[66:67], v[236:237]
	v_pk_mul_f32 v[44:45], v[42:43], v[44:45]
	v_mul_f32_e32 v42, v94, v95
	v_pk_mul_f32 v[94:95], v[164:165], v[98:99]
	v_mul_f32_e32 v39, v39, v47
	v_mov_b32_e32 v139, v94
	v_pk_mul_f32 v[66:67], v[124:125], v[138:139]
	v_mul_f32_e32 v39, v39, v113
	v_mov_b32_e32 v119, v67
	v_pk_mul_f32 v[100:101], v[116:117], v[118:119]
	v_mul_f32_e32 v43, v58, v59
	v_cndmask_b32_e64 v59, 0, v39, s[44:45]
	v_mov_b32_e32 v109, v101
	v_mul_f32_e32 v39, v66, v67
	v_mul_f32_e32 v61, v87, v245
	v_pk_mul_f32 v[106:107], v[106:107], v[108:109]
	v_cndmask_b32_e64 v66, 0, v39, s[62:63]
	v_mul_f32_e32 v39, v100, v101
	v_pk_mul_f32 v[56:57], v[56:57], v[60:61]
	v_cndmask_b32_e64 v101, 0, v39, s[56:57]
	v_mul_f32_e32 v39, v106, v107
	v_mov_b32_e32 v51, v57
	v_cndmask_b32_e64 v100, 0, v39, s[50:51]
	v_pk_mul_f32 v[94:95], v[158:159], v[94:95]
	v_mul_f32_e32 v39, v234, v235
	v_pk_mul_f32 v[48:49], v[48:49], v[50:51]
	v_cndmask_b32_e64 v98, 0, v95, s[80:81]
	v_cndmask_b32_e64 v95, 0, v39, s[78:79]
	v_mul_f32_e32 v39, v103, v237
	v_mov_b32_e32 v47, v49
	v_cndmask_b32_e64 v67, 0, v94, s[86:87]
	v_cndmask_b32_e64 v94, 0, v39, s[76:77]
	v_mul_f32_e32 v39, v93, v99
	v_pk_mul_f32 v[40:41], v[40:41], v[46:47]
	v_cndmask_b32_e64 v99, 0, v39, s[70:71]
	v_mov_b32_e32 v39, v41
	v_pk_mul_f32 v[46:47], v[36:37], v[38:39]
	v_mul_f32_e32 v36, v56, v57
	v_mul_f32_e32 v38, v40, v41
	v_pk_mov_b32 v[40:41], v[86:87], v[128:129] op_sel:[1,0]
	v_cndmask_b32_e64 v37, 0, v36, s[34:35]
	v_mul_f32_e32 v36, v48, v49
	v_pk_mul_f32 v[48:49], v[40:41], v[156:157]
	v_cndmask_b32_e64 v39, 0, v38, s[26:27]
	v_pk_mul_f32 v[50:51], v[162:163], v[48:49]
	v_mul_f32_e32 v38, v46, v47
	v_mov_b32_e32 v103, v50
	v_pk_mul_f32 v[40:41], v[96:97], v[102:103]
	v_cndmask_b32_e64 v151, 1.0, v135, s[18:19]
	v_mov_b32_e32 v93, v41
	v_pk_mul_f32 v[46:47], v[62:63], v[92:93]
	v_mul_f32_e32 v40, v40, v41
	v_mov_b32_e32 v55, v47
	v_pk_mul_f32 v[52:53], v[52:53], v[54:55]
	v_mul_f32_e32 v41, v46, v47
	v_mov_b32_e32 v149, v87
	v_cndmask_b32_e64 v47, 0, v41, s[38:39]
	v_mul_f32_e32 v41, v52, v53
	v_pk_mul_f32 v[50:51], v[152:153], v[50:51]
	v_pk_mul_f32 v[52:53], v[148:149], v[150:151]
	v_cndmask_b32_e64 v46, 0, v41, s[30:31]
	v_cndmask_b32_e64 v41, 0, v50, s[74:75]
	v_mul_f32_e32 v50, v147, v155
	v_mov_b32_e32 v147, v53
	v_pk_mul_f32 v[54:55], v[144:145], v[146:147]
	v_cndmask_b32_e64 v48, 0, v51, s[72:73]
	v_cndmask_b32_e64 v51, 0, v50, s[60:61]
	v_mul_f32_e32 v50, v143, v157
	v_mov_b32_e32 v143, v55
	v_pk_mul_f32 v[56:57], v[140:141], v[142:143]
	v_cndmask_b32_e64 v65, 0, v43, s[36:37]
	v_mul_f32_e32 v43, v44, v45
	v_pk_mul_f32 v[44:45], v[132:133], v[114:115]
	v_mul_f32_e32 v49, v137, v49
	v_mov_b32_e32 v137, v57
	v_mul_f32_e32 v52, v52, v53
	v_cndmask_b32_e64 v64, 0, v43, s[24:25]
	v_cndmask_b32_e64 v43, 0, v44, s[84:85]
	v_mul_f32_e32 v44, v120, v121
	v_pk_mul_f32 v[60:61], v[130:131], v[136:137]
	v_cndmask_b32_e64 v53, 0, v52, s[68:69]
	v_mul_f32_e32 v52, v54, v55
	v_mul_f32_e32 v54, v56, v57
	v_cndmask_b32_e64 v58, 0, v45, s[82:83]
	v_cndmask_b32_e64 v45, 0, v44, s[52:53]
	v_mul_f32_e32 v44, v110, v111
	v_readlane_b32 s72, v250, 13
	v_cndmask_b32_e64 v55, 0, v54, s[64:65]
	v_mul_f32_e32 v54, v60, v61
	v_mul_f32_e32 v56, v104, v129
	v_cndmask_b32_e64 v42, 0, v42, s[40:41]
	s_movk_i32 s36, 0x1ff
	v_cndmask_b32_e64 v44, 0, v44, s[48:49]
	v_cndmask_b32_e64 v36, 0, v36, s[28:29]
	v_readlane_b32 s28, v250, 31
	v_cndmask_b32_e32 v38, 0, v38, vcc
	v_cndmask_b32_e64 v40, 0, v40, s[42:43]
	s_mov_b64 s[38:39], 0x2000
	v_readlane_b32 s73, v250, 14
	v_readlane_b32 s74, v250, 15
	v_readlane_b32 s75, v250, 16
	v_readlane_b32 s76, v250, 17
	v_readlane_b32 s77, v250, 18
	v_readlane_b32 s78, v250, 19
	v_readlane_b32 s79, v250, 20
	v_readlane_b32 s80, v250, 21
	v_readlane_b32 s81, v250, 22
	v_readlane_b32 s82, v250, 23
	v_readlane_b32 s83, v250, 24
	v_readlane_b32 s84, v250, 25
	v_readlane_b32 s85, v250, 26
	v_readlane_b32 s86, v250, 27
	v_readlane_b32 s87, v250, 28
	v_cndmask_b32_e64 v50, 0, v50, s[54:55]
	v_cndmask_b32_e64 v49, 0, v49, s[46:47]
	v_cndmask_b32_e64 v52, 0, v52, s[66:67]
	s_mov_b32 s40, 0x3fb8aa3b
	v_readlane_b32 s31, v250, 30
	v_readlane_b32 s30, v250, 29
	v_cndmask_b32_e64 v54, 0, v54, s[58:59]
	v_mul_f32_e32 v56, v56, v105
	s_mov_b64 s[24:25], 0
; __device__ __forceinline__ float ex2(float x) { return __builtin_amdgcn_exp2f(x); }
; __device__ __forceinline__ float rcp(float x) { return __builtin_amdgcn_rcpf(x); }
; template <bool MK> __device__ __forceinline__ void sb_scan(f32x16& s0, f32x16& s1, int db, int hi, float& R) {
;             f32x16 k0, k1;
; #pragma unroll
;             for (int r = 0; r < 16; ++r) {
;                 const float e0 = ex2(fminf(s0[r], 80.f)), e1 = ex2(fminf(s1[r], 80.f));
;                 const float p0 = rcp(1.0f + e0), p1 = rcp(1.0f + e1);
;                 s0[r] = e0 * p0; s1[r] = e1 * p1;
;                 k0[r] = (!MK || KKOF(0, r) < db) ? p0 : 1.0f; k1[r] = (!MK || KKOF(1, r) < db) ? p1 : 1.0f;
;             }
;             float g4[8], pg[8], E[8];
; #pragma unroll
;             for (int k4 = 0; k4 < 4; ++k4) { g4[k4] = (k0[4 * k4] * k0[4 * k4 + 1]) * (k0[4 * k4 + 2] * k0[4 * k4 + 3]); g4[4 + k4] = (k1[4 * k4] * k1[4 * k4 + 1]) * (k1[4 * k4 + 2] * k1[4 * k4 + 3]); }
; #pragma unroll
;             for (int G = 0; G < 8; ++G) pg[G] = __shfl_xor(g4[G], 32);
;             E[7] = 1.0f;
; #pragma unroll
;             for (int G = 6; G >= 0; --G) E[G] = E[G + 1] * (g4[G + 1] * pg[G + 1]);
;             const float T = E[0] * (g4[0] * pg[0]);
.LBB0_626:
	s_andn2_b64 vcc, exec, s[24:25]
	s_cbranch_vccnz .LBB0_628
	v_exp_f32_e32 v42, v232
	v_exp_f32_e32 v36, v233
	v_add_f32_e32 v37, 1.0, v42
	v_rcp_f32_e32 v44, v37
	v_add_f32_e32 v38, 1.0, v36
	v_exp_f32_e32 v59, v231
	v_exp_f32_e32 v39, v230
	v_rcp_f32_e32 v40, v38
	v_exp_f32_e32 v66, v229
	v_exp_f32_e32 v92, v228
	v_add_f32_e32 v37, 1.0, v59
	v_exp_f32_e32 v99, v227
	v_rcp_f32_e32 v64, v37
	v_add_f32_e32 v37, 1.0, v39
	v_exp_f32_e32 v103, v226
	v_rcp_f32_e32 v48, v37
	v_add_f32_e32 v37, 1.0, v66
	v_exp_f32_e32 v120, v225
	v_rcp_f32_e32 v94, v37
	v_add_f32_e32 v37, 1.0, v92
	v_exp_f32_e32 v46, v224
	v_rcp_f32_e32 v41, v37
	v_add_f32_e32 v37, 1.0, v99
	v_exp_f32_e32 v125, v223
	v_rcp_f32_e32 v100, v37
	v_add_f32_e32 v37, 1.0, v103
	v_exp_f32_e32 v53, v222
	v_rcp_f32_e32 v49, v37
	v_add_f32_e32 v37, 1.0, v120
	v_exp_f32_e32 v128, v221
	v_rcp_f32_e32 v122, v37
	v_add_f32_e32 v37, 1.0, v46
	v_exp_f32_e32 v108, v220
	v_rcp_f32_e32 v56, v37
	v_add_f32_e32 v37, 1.0, v125
	v_exp_f32_e32 v131, v219
	v_rcp_f32_e32 v126, v37
	v_add_f32_e32 v37, 1.0, v53
	v_exp_f32_e32 v113, v217
	v_rcp_f32_e32 v62, v37
	v_add_f32_e32 v37, 1.0, v128
	v_exp_f32_e32 v132, v216
	v_rcp_f32_e32 v123, v37
	v_add_f32_e32 v37, 1.0, v108
	v_exp_f32_e32 v60, v215
	v_rcp_f32_e32 v57, v37
	v_add_f32_e32 v37, 1.0, v131
	v_exp_f32_e32 v137, v214
	v_rcp_f32_e32 v127, v37
	v_add_f32_e32 v37, 1.0, v113
	v_exp_f32_e32 v97, v213
	v_rcp_f32_e32 v63, v37
	v_add_f32_e32 v37, 1.0, v132
	v_exp_f32_e32 v140, v212
	v_rcp_f32_e32 v134, v37
	v_add_f32_e32 v37, 1.0, v60
	v_exp_f32_e32 v116, v211
	v_rcp_f32_e32 v50, v37
	v_add_f32_e32 v37, 1.0, v137
	v_exp_f32_e32 v143, v210
	v_rcp_f32_e32 v138, v37
	v_add_f32_e32 v37, 1.0, v97
	v_exp_f32_e32 v119, v209
	v_rcp_f32_e32 v54, v37
	v_add_f32_e32 v37, 1.0, v140
	v_exp_f32_e32 v144, v208
	v_rcp_f32_e32 v135, v37
	v_add_f32_e32 v37, 1.0, v116
	v_exp_f32_e32 v106, v207
	v_rcp_f32_e32 v104, v37
	v_add_f32_e32 v37, 1.0, v143
	v_exp_f32_e32 v149, v206
	v_rcp_f32_e32 v139, v37
	v_add_f32_e32 v37, 1.0, v119
	v_exp_f32_e32 v111, v205
	v_rcp_f32_e32 v114, v37
	v_add_f32_e32 v37, 1.0, v144
	v_exp_f32_e32 v38, v204
	v_rcp_f32_e32 v146, v37
	v_add_f32_e32 v37, 1.0, v106
	v_exp_f32_e32 v43, v203
	v_rcp_f32_e32 v51, v37
	v_add_f32_e32 v37, 1.0, v149
	v_exp_f32_e32 v154, v202
	v_rcp_f32_e32 v150, v37
	v_add_f32_e32 v37, 1.0, v111
	v_exp_f32_e32 v86, v187
	v_rcp_f32_e32 v55, v37
	v_add_f32_e32 v37, 1.0, v38
	v_rcp_f32_e32 v152, v37
	v_add_f32_e32 v37, 1.0, v43
	v_rcp_f32_e32 v105, v37
	v_add_f32_e32 v37, 1.0, v154
	v_rcp_f32_e32 v156, v37
	v_add_f32_e32 v37, 1.0, v86
	v_rcp_f32_e32 v115, v37
	v_pk_mul_f32 v[164:165], v[50:51], v[54:55]
	v_pk_mul_f32 v[162:163], v[56:57], v[62:63]
	v_pk_mul_f32 v[158:159], v[40:41], v[48:49]
	v_pk_mul_f32 v[202:203], v[104:105], v[114:115]
	v_mul_f32_e32 v37, v162, v163
	v_pk_mul_f32 v[164:165], v[164:165], v[202:203]
	ds_bpermute_b32 v202, v201, v164
	ds_bpermute_b32 v203, v201, v165
	v_pk_mul_f32 v[158:159], v[158:159], v[158:159] op_sel:[0,1] op_sel_hi:[1,0]
	ds_bpermute_b32 v47, v201, v37
	ds_bpermute_b32 v151, v201, v158
	v_mov_b32_e32 v147, v158
	s_waitcnt lgkmcnt(2)
	v_pk_mul_f32 v[164:165], v[164:165], v[202:203]
	v_pk_mul_f32 v[162:163], v[134:135], v[138:139]
	v_pk_mul_f32 v[204:205], v[164:165], v[164:165] op_sel:[0,1] op_sel_hi:[1,0]
	s_waitcnt lgkmcnt(1)
	v_mul_f32_e32 v153, v37, v47
	v_mov_b32_e32 v157, v204
	v_pk_mul_f32 v[206:207], v[152:153], v[156:157]
	s_waitcnt lgkmcnt(0)
	v_pk_mul_f32 v[158:159], v[146:147], v[150:151]
	v_pk_mul_f32 v[160:161], v[122:123], v[126:127]
	v_pk_mul_f32 v[158:159], v[158:159], v[206:207]
	ds_bpermute_b32 v37, v201, v158
	v_mul_f32_e32 v45, v162, v163
	ds_bpermute_b32 v52, v201, v45
	v_pk_mul_f32 v[160:161], v[160:161], v[160:161] op_sel:[0,1] op_sel_hi:[1,0]
	ds_bpermute_b32 v65, v201, v160
	s_waitcnt lgkmcnt(2)
	v_mul_f32_e32 v58, v158, v37
	v_mul_f32_e32 v101, v58, v159
	s_waitcnt lgkmcnt(1)
	v_mul_f32_e32 v95, v45, v52
	v_mov_b32_e32 v45, v160
	v_pk_mul_f32 v[162:163], v[94:95], v[100:101]
	s_waitcnt lgkmcnt(0)
	v_pk_mul_f32 v[160:161], v[44:45], v[64:65]
	v_cndmask_b32_e64 v129, 1.0, v65, s[18:19]
	v_pk_mul_f32 v[160:161], v[160:161], v[162:163]
	ds_bpermute_b32 v153, v201, v160
	v_mul_f32_e32 v95, v87, v161
	v_mul_f32_e32 v162, v43, v105
	v_mov_b32_e32 v43, v94
	v_mul_f32_e32 v158, v38, v152
	s_waitcnt lgkmcnt(0)
; template <bool MK> __device__ __forceinline__ void sb_scan(f32x16& s0, f32x16& s1, int db, int hi, float& R) {
;     ...
;             E[7] = 1.0f;
; #pragma unroll
;             for (int G = 6; G >= 0; --G) E[G] = E[G + 1] * (g4[G + 1] * pg[G + 1]);
;             const float T = E[0] * (g4[0] * pg[0]);
; #pragma unroll
;             for (int G = 0; G < 8; ++G) {
;                 const float base = R * E[G] * (hi == 0 ? pg[G] : 1.0f);
;                 const int k4 = G & 3;
;                 if (G < 4) {
;                     const float u3 = base, u2 = u3 * k0[4 * k4 + 3], u1 = u2 * k0[4 * k4 + 2], u0 = u1 * k0[4 * k4 + 1];
;                     s0[4 * k4 + 3] = (!MK || KKOF(0, 4 * k4 + 3) < db) ? s0[4 * k4 + 3] * u3 : 0.f;
;                     s0[4 * k4 + 2] = (!MK || KKOF(0, 4 * k4 + 2) < db) ? s0[4 * k4 + 2] * u2 : 0.f;
;                     s0[4 * k4 + 1] = (!MK || KKOF(0, 4 * k4 + 1) < db) ? s0[4 * k4 + 1] * u1 : 0.f;
;                     s0[4 * k4 + 0] = (!MK || KKOF(0, 4 * k4 + 0) < db) ? s0[4 * k4 + 0] * u0 : 0.f;
;                 } else {
;                     const float u3 = base, u2 = u3 * k1[4 * k4 + 3], u1 = u2 * k1[4 * k4 + 2], u0 = u1 * k1[4 * k4 + 1];
;                     s1[4 * k4 + 3] = (!MK || KKOF(1, 4 * k4 + 3) < db) ? s1[4 * k4 + 3] * u3 : 0.f;
;                     s1[4 * k4 + 2] = (!MK || KKOF(1, 4 * k4 + 2) < db) ? s1[4 * k4 + 2] * u2 : 0.f;
;                     s1[4 * k4 + 1] = (!MK || KKOF(1, 4 * k4 + 1) < db) ? s1[4 * k4 + 1] * u1 : 0.f;
;                     s1[4 * k4 + 0] = (!MK || KKOF(1, 4 * k4 + 0) < db) ? s1[4 * k4 + 0] * u0 : 0.f;
;                 }
;             }
;             R *= T;
	v_cndmask_b32_e64 v67, 1.0, v153, s[18:19]
	v_pk_mul_f32 v[66:67], v[66:67], v[94:95]
	v_mov_b32_e32 v38, v127
	v_mov_b32_e32 v98, v67
	v_pk_mul_f32 v[98:99], v[100:101], v[98:99] op_sel_hi:[0,1]
	v_mov_b32_e32 v45, v98
	v_pk_mul_f32 v[42:43], v[42:43], v[44:45]
	v_mov_b32_e32 v121, v123
	v_mov_b32_e32 v58, v43
	v_pk_mul_f32 v[44:45], v[64:65], v[58:59] op_sel_hi:[0,1]
	v_mul_f32_e32 v59, v87, v163
	v_mov_b32_e32 v58, v123
	v_pk_mul_f32 v[94:95], v[128:129], v[58:59]
	v_cndmask_b32_e64 v141, 1.0, v52, s[18:19]
	v_mov_b32_e32 v130, v95
	v_pk_mul_f32 v[128:129], v[38:39], v[130:131] op_sel_hi:[0,1]
	v_mov_b32_e32 v123, v128
	v_pk_mul_f32 v[58:59], v[120:121], v[122:123]
	v_mul_f32_e32 v65, v87, v101
	v_mov_b32_e32 v124, v59
	v_pk_mul_f32 v[120:121], v[126:127], v[124:125] op_sel_hi:[0,1]
	v_mov_b32_e32 v64, v135
	v_pk_mul_f32 v[122:123], v[140:141], v[64:65]
	v_pk_mul_f32 v[58:59], v[120:121], v[58:59]
	v_cndmask_b32_e64 v93, 1.0, v151, s[18:19]
	v_mul_f32_e32 v121, v87, v207
	v_mov_b32_e32 v120, v41
	v_mov_b32_e32 v38, v139
	v_mov_b32_e32 v142, v123
	v_pk_mul_f32 v[92:93], v[92:93], v[120:121]
	v_pk_mul_f32 v[124:125], v[38:39], v[142:143] op_sel_hi:[0,1]
	v_mov_b32_e32 v38, v49
	v_mov_b32_e32 v102, v93
	v_pk_mul_f32 v[102:103], v[38:39], v[102:103] op_sel_hi:[0,1]
	v_cndmask_b32_e64 v155, 1.0, v37, s[18:19]
	v_mov_b32_e32 v37, v41
	v_mov_b32_e32 v41, v102
	v_pk_mul_f32 v[36:37], v[36:37], v[40:41]
	v_cndmask_b32_e64 v109, 1.0, v47, s[18:19]
	v_mul_f32_e32 v41, v87, v204
	v_mov_b32_e32 v40, v57
	v_mov_b32_e32 v38, v37
	v_pk_mul_f32 v[40:41], v[108:109], v[40:41]
	v_pk_mul_f32 v[38:39], v[48:49], v[38:39] op_sel_hi:[0,1]
	v_mov_b32_e32 v48, v63
	v_mov_b32_e32 v112, v41
	v_pk_mul_f32 v[48:49], v[48:49], v[112:113] op_sel_hi:[0,1]
	v_mov_b32_e32 v47, v57
	v_mov_b32_e32 v57, v48
	v_pk_mul_f32 v[46:47], v[46:47], v[56:57]
	v_cndmask_b32_e64 v117, 1.0, v202, s[18:19]
	v_mul_f32_e32 v57, v87, v165
	v_mov_b32_e32 v56, v104
	v_pk_mul_f32 v[56:57], v[116:117], v[56:57]
	v_mov_b32_e32 v52, v47
	v_mov_b32_e32 v118, v57
	v_pk_mul_f32 v[52:53], v[62:63], v[52:53] op_sel_hi:[0,1]
	v_pk_mul_f32 v[62:63], v[114:115], v[118:119] op_sel_hi:[0,1]
	v_mov_b32_e32 v61, v104
	v_mov_b32_e32 v108, v50
	v_mov_b32_e32 v109, v62
	v_mul_f32_e32 v157, v87, v159
	v_pk_mul_f32 v[60:61], v[60:61], v[108:109]
	v_cndmask_b32_e64 v109, 1.0, v203, s[18:19]
	v_mov_b32_e32 v108, v115
	v_pk_mul_f32 v[64:65], v[154:155], v[156:157]
	v_pk_mul_f32 v[108:109], v[86:87], v[108:109]
	v_mul_f32_e32 v130, v156, v65
	v_mul_f32_e32 v112, v115, v109
	v_mov_b32_e32 v133, v135
	v_mov_b32_e32 v135, v124
	v_mov_b32_e32 v145, v152
	v_mov_b32_e32 v147, v130
	v_mov_b32_e32 v107, v105
	v_mov_b32_e32 v50, v51
	v_mov_b32_e32 v51, v112
	v_pk_mul_f32 v[100:101], v[132:133], v[134:135]
	v_pk_mul_f32 v[132:133], v[144:145], v[146:147]
	v_pk_mul_f32 v[104:105], v[106:107], v[50:51]
	v_mov_b32_e32 v136, v101
	v_mov_b32_e32 v148, v133
	v_mov_b32_e32 v96, v61
	v_mov_b32_e32 v50, v55
	v_mov_b32_e32 v110, v105
	v_pk_mul_f32 v[126:127], v[138:139], v[136:137] op_sel_hi:[0,1]
	v_mov_b32_e32 v159, v64
	v_mov_b32_e32 v131, v65
	v_pk_mul_f32 v[134:135], v[150:151], v[148:149] op_sel_hi:[0,1]
	v_pk_mul_f32 v[96:97], v[54:55], v[96:97] op_sel_hi:[0,1]
	v_mov_b32_e32 v163, v108
	v_mov_b32_e32 v113, v109
	v_pk_mul_f32 v[54:55], v[50:51], v[110:111] op_sel_hi:[0,1]
	v_pk_mul_f32 v[50:51], v[62:63], v[56:57]
	v_mul_f32_e32 v56, v160, v153
	v_pk_mul_f32 v[64:65], v[44:45], v[42:43]
	v_pk_mul_f32 v[42:43], v[98:99], v[66:67]
	v_pk_mul_f32 v[44:45], v[128:129], v[94:95]
	v_pk_mul_f32 v[100:101], v[126:127], v[100:101]
	v_pk_mul_f32 v[66:67], v[124:125], v[122:123]
	v_pk_mul_f32 v[98:99], v[134:135], v[132:133]
	v_pk_mul_f32 v[94:95], v[158:159], v[130:131]
	v_pk_mul_f32 v[38:39], v[38:39], v[36:37]
	v_pk_mul_f32 v[36:37], v[102:103], v[92:93]
	v_pk_mul_f32 v[46:47], v[52:53], v[46:47]
	v_pk_mul_f32 v[40:41], v[48:49], v[40:41]
	v_pk_mul_f32 v[48:49], v[96:97], v[60:61]
	v_pk_mul_f32 v[54:55], v[54:55], v[104:105]
	v_pk_mul_f32 v[52:53], v[162:163], v[112:113]
	v_mul_f32_e32 v56, v56, v161
